# variant: s_setprio 1 placed before the load segment's final waits
# baseline (speedup 1.0000x reference)
; #define PG8_STAGE(bufoff, gbase, voff) do { _Pragma("unroll") for (int _i = 0; _i < 2; ++_i) \
;         __builtin_amdgcn_global_load_lds((const unsigned*)((const char*)(gbase) + (voff)[_i]), (PG8_LAS unsigned*)(lds + (bufoff) + ldsw + _i * 8192), 16, 0, 0); } while (0)
; #define PG8_LDA(dst, b, h) do { _Pragma("unroll") for (int m = 0; m < 4; ++m) _Pragma("unroll") for (int k = 0; k < 2; ++k) dst[m][k] = *(const PG8_LAS bf16x8*)(lds + PG8_SA(b, h) + aoff + m * 2048 + k * 1024); } while (0)
; #define PG8_LDB(dst, b, h) do { _Pragma("unroll") for (int n = 0; n < 2; ++n) _Pragma("unroll") for (int k = 0; k < 2; ++k) dst[n][k] = *(const PG8_LAS bf16x8*)(lds + PG8_SB(b, h) + boff + n * 2048 + k * 1024); } while (0)
; #define PG8_MMA(ai, bj, At, Bt) do { __builtin_amdgcn_s_setprio(1); _Pragma("unroll") for (int m = 0; m < 4; ++m) _Pragma("unroll") for (int n = 0; n < 2; ++n) _Pragma("unroll") for (int k = 0; k < 2; ++k) \
;         acc[ai][bj][m][n] = __builtin_amdgcn_mfma_f32_16x16x32_bf16(Bt[n][k], At[m][k], acc[ai][bj][m][n], 0, 0, 0); __builtin_amdgcn_s_setprio(0); } while (0)
; #define PG8_WAIT_V(n) asm volatile("s_waitcnt vmcnt(" #n ")" ::: "memory")
; #define PG8_WAIT_L(n) asm volatile("s_waitcnt lgkmcnt(" #n ")" ::: "memory")
; template <class Epi, class Sched, bool ALIGN_EPI = false, bool SP2 = false>
; __device__ __forceinline__ void gemm_phase(PG8_LAS unsigned char* lds, const Gemm g, const Sched& S, const Epi& E) {
;     ...
;             const bool last = (t == nt - 2);
;             const char* a1 = cA + (size_t)(t + 1) * kstep;
;             const char* a2 = last ? nA : cA + (size_t)(t + 2) * kstep; const char* b2 = last ? nB : cB + (size_t)(t + 2) * kstep;
;             const char* a3 = a2 + kstep; const char* b3 = b2 + kstep;
;             if (last && has_next) S.a_ready(nxt);
;             if constexpr (SP2) {
;             PG8_LDB(B0, 0, 0); PG8_LDB(B1, 0, 1); PG8_SCHED; PG8_LDA(At, 0, 0); PG8_STAGE(PG8_SA(1, 1), a1 + hstep, voffA);
;             PG8_WAIT_V(8); PG8_WAIT_L(0); PG8_BAR; PG8_MMA(0, 0, At, B0); PG8_MMA(0, 1, At, B1); PG8_BAR; PG8_SCHED;
;             PG8_LDA(At, 0, 1); PG8_STAGE(PG8_SB(0, 0), b2, voffB); PG8_STAGE(PG8_SB(0, 1), b2 + hstep, voffB); PG8_STAGE(PG8_SA(0, 0), a2, voffA);
;             PG8_WAIT_V(8); PG8_WAIT_L(0); PG8_BAR; PG8_MMA(1, 0, At, B0); PG8_MMA(1, 1, At, B1); PG8_BAR; PG8_SCHED;
.LBB0_63:
	s_add_i32 s66, s46, 2
	s_add_u32 s10, s44, 0x80
	s_addc_u32 s11, s45, 0
	s_add_i32 s67, 0, 0x10000
	s_cmp_eq_u32 s74, s46
	s_cselect_b32 s47, s63, s11
	s_cselect_b32 s46, s62, s10
	s_cselect_b32 s79, s65, s20
	s_cselect_b32 s78, s64, s19
	s_add_i32 s10, 0, 0x14000
	v_add_u32_e32 v140, s67, v183
	v_add_u32_e32 v166, s10, v183
	ds_read_b128 v[128:131], v140
	ds_read_b128 v[132:135], v140 offset:1024
	ds_read_b128 v[136:139], v140 offset:2048
	ds_read_b128 v[140:143], v140 offset:3072
	ds_read_b128 v[144:147], v166
	ds_read_b128 v[148:151], v166 offset:1024
	ds_read_b128 v[152:155], v166 offset:2048
	ds_read_b128 v[166:169], v166 offset:3072
	v_lshl_add_u64 v[190:191], s[44:45], 0, v[162:163]
	s_add_i32 m0, s23, 0xc000
	ds_read_b128 v[170:173], v185
	ds_read_b128 v[174:177], v185 offset:1024
	ds_read_b128 v[178:181], v185 offset:2048
	ds_read_b128 v[186:189], v185 offset:3072
	ds_read_b128 v[194:197], v185 offset:4096
	ds_read_b128 v[198:201], v185 offset:5120
	ds_read_b128 v[202:205], v185 offset:6144
	ds_read_b128 v[206:209], v185 offset:7168
	global_load_lds_dwordx4 v[190:191], off
	v_lshl_add_u64 v[190:191], s[44:45], 0, v[164:165]
	s_add_i32 m0, s23, 0xe000
	s_nop 0
	global_load_lds_dwordx4 v[190:191], off
	s_setprio 1
	s_waitcnt vmcnt(8)
	s_waitcnt lgkmcnt(0)
	s_barrier
	v_mfma_f32_16x16x32_bf16 v[124:127], v[128:131], v[170:173], v[124:127]
	v_mfma_f32_16x16x32_bf16 v[120:123], v[136:139], v[170:173], v[120:123]
	v_mfma_f32_16x16x32_bf16 v[108:111], v[128:131], v[178:181], v[108:111]
	v_mfma_f32_16x16x32_bf16 v[104:107], v[136:139], v[178:181], v[104:107]
	v_mfma_f32_16x16x32_bf16 v[92:95], v[128:131], v[194:197], v[92:95]
	v_mfma_f32_16x16x32_bf16 v[88:91], v[136:139], v[194:197], v[88:91]
	v_mfma_f32_16x16x32_bf16 v[76:79], v[128:131], v[202:205], v[76:79]
	v_mfma_f32_16x16x32_bf16 v[72:75], v[136:139], v[202:205], v[72:75]
	v_mfma_f32_16x16x32_bf16 v[124:127], v[132:135], v[174:177], v[124:127]
	v_mfma_f32_16x16x32_bf16 v[120:123], v[140:143], v[174:177], v[120:123]
	v_mfma_f32_16x16x32_bf16 v[108:111], v[132:135], v[186:189], v[108:111]
	v_mfma_f32_16x16x32_bf16 v[104:107], v[140:143], v[186:189], v[104:107]
	v_mfma_f32_16x16x32_bf16 v[92:95], v[132:135], v[198:201], v[92:95]
	v_mfma_f32_16x16x32_bf16 v[88:91], v[140:143], v[198:201], v[88:91]
	v_mfma_f32_16x16x32_bf16 v[76:79], v[132:135], v[206:209], v[76:79]
	v_mfma_f32_16x16x32_bf16 v[72:75], v[140:143], v[206:209], v[72:75]
	s_setprio 0
	s_setprio 1
	v_mfma_f32_16x16x32_bf16 v[116:119], v[144:147], v[170:173], v[116:119]
	v_mfma_f32_16x16x32_bf16 v[112:115], v[152:155], v[170:173], v[112:115]
	v_mfma_f32_16x16x32_bf16 v[100:103], v[144:147], v[178:181], v[100:103]
	v_mfma_f32_16x16x32_bf16 v[96:99], v[152:155], v[178:181], v[96:99]
	v_mfma_f32_16x16x32_bf16 v[84:87], v[144:147], v[194:197], v[84:87]
	v_mfma_f32_16x16x32_bf16 v[80:83], v[152:155], v[194:197], v[80:83]
	v_mfma_f32_16x16x32_bf16 v[68:71], v[144:147], v[202:205], v[68:71]
	v_mfma_f32_16x16x32_bf16 v[64:67], v[152:155], v[202:205], v[64:67]
	v_mfma_f32_16x16x32_bf16 v[116:119], v[148:151], v[174:177], v[116:119]
	v_mfma_f32_16x16x32_bf16 v[112:115], v[166:169], v[174:177], v[112:115]
	v_mfma_f32_16x16x32_bf16 v[100:103], v[148:151], v[186:189], v[100:103]
	v_mfma_f32_16x16x32_bf16 v[96:99], v[166:169], v[186:189], v[96:99]
	v_mfma_f32_16x16x32_bf16 v[84:87], v[148:151], v[198:201], v[84:87]
	v_mfma_f32_16x16x32_bf16 v[80:83], v[166:169], v[198:201], v[80:83]
	v_mfma_f32_16x16x32_bf16 v[68:71], v[148:151], v[206:209], v[68:71]
	v_mfma_f32_16x16x32_bf16 v[64:67], v[166:169], v[206:209], v[64:67]
	s_barrier
	s_setprio 0
	s_add_i32 s11, s67, s22
	v_lshl_add_u64 v[190:191], s[78:79], 0, v[192:193]
	s_mov_b32 m0, s11
	ds_read_b128 v[170:173], v185 offset:16384
	ds_read_b128 v[174:177], v185 offset:17408
	ds_read_b128 v[178:181], v185 offset:18432
	ds_read_b128 v[186:189], v185 offset:19456
	ds_read_b128 v[194:197], v185 offset:20480
	ds_read_b128 v[198:201], v185 offset:21504
	ds_read_b128 v[202:205], v185 offset:22528
	ds_read_b128 v[206:209], v185 offset:23552
	global_load_lds_dwordx4 v[190:191], off
	s_add_i32 m0, s11, 0x2000
	v_lshl_add_u64 v[210:211], s[78:79], 0, v[160:161]
	s_add_u32 s78, s78, s52
	s_addc_u32 s79, s79, 0
	s_add_i32 s10, s10, s22
	global_load_lds_dwordx4 v[210:211], off
	v_lshl_add_u64 v[212:213], s[78:79], 0, v[192:193]
	s_mov_b32 m0, s10
	v_lshl_add_u64 v[214:215], s[78:79], 0, v[160:161]
	global_load_lds_dwordx4 v[212:213], off
	s_add_i32 m0, s10, 0x2000
	v_lshl_add_u64 v[216:217], s[46:47], 0, v[156:157]
	global_load_lds_dwordx4 v[214:215], off
	s_mov_b32 m0, s23
	v_lshl_add_u64 v[218:219], s[46:47], 0, v[158:159]
	global_load_lds_dwordx4 v[216:217], off
	s_mov_b32 m0, s51
	s_nop 0
	global_load_lds_dwordx4 v[218:219], off
	s_setprio 1
	s_waitcnt vmcnt(8)
	s_waitcnt lgkmcnt(0)
	s_barrier
; #define PG8_STAGE(bufoff, gbase, voff) do { _Pragma("unroll") for (int _i = 0; _i < 2; ++_i) \
;         __builtin_amdgcn_global_load_lds((const unsigned*)((const char*)(gbase) + (voff)[_i]), (PG8_LAS unsigned*)(lds + (bufoff) + ldsw + _i * 8192), 16, 0, 0); } while (0)
; #define PG8_LDA(dst, b, h) do { _Pragma("unroll") for (int m = 0; m < 4; ++m) _Pragma("unroll") for (int k = 0; k < 2; ++k) dst[m][k] = *(const PG8_LAS bf16x8*)(lds + PG8_SA(b, h) + aoff + m * 2048 + k * 1024); } while (0)
; #define PG8_LDB(dst, b, h) do { _Pragma("unroll") for (int n = 0; n < 2; ++n) _Pragma("unroll") for (int k = 0; k < 2; ++k) dst[n][k] = *(const PG8_LAS bf16x8*)(lds + PG8_SB(b, h) + boff + n * 2048 + k * 1024); } while (0)
; #define PG8_MMA(ai, bj, At, Bt) do { __builtin_amdgcn_s_setprio(1); _Pragma("unroll") for (int m = 0; m < 4; ++m) _Pragma("unroll") for (int n = 0; n < 2; ++n) _Pragma("unroll") for (int k = 0; k < 2; ++k) \
;         acc[ai][bj][m][n] = __builtin_amdgcn_mfma_f32_16x16x32_bf16(Bt[n][k], At[m][k], acc[ai][bj][m][n], 0, 0, 0); __builtin_amdgcn_s_setprio(0); } while (0)
; #define PG8_WAIT_V(n) asm volatile("s_waitcnt vmcnt(" #n ")" ::: "memory")
; #define PG8_WAIT_L(n) asm volatile("s_waitcnt lgkmcnt(" #n ")" ::: "memory")
; #define PG8_BAR __builtin_amdgcn_s_barrier()
; #define PG8_SCHED __builtin_amdgcn_sched_barrier(0)
; template <class Epi, class Sched, bool ALIGN_EPI = false, bool SP2 = false>
; __device__ __forceinline__ void gemm_phase(PG8_LAS unsigned char* lds, const Gemm g, const Sched& S, const Epi& E) {
;     ...
;             PG8_WAIT_V(8); PG8_WAIT_L(0); PG8_BAR; PG8_MMA(1, 0, At, B0); PG8_MMA(1, 1, At, B1); PG8_BAR; PG8_SCHED;
;             PG8_LDB(B0, 1, 0); PG8_LDB(B1, 1, 1); PG8_SCHED; PG8_LDA(At, 1, 0); PG8_STAGE(PG8_SA(0, 1), a2 + hstep, voffA);
;             PG8_WAIT_V(8); PG8_WAIT_L(0); PG8_BAR; PG8_MMA(0, 0, At, B0); PG8_MMA(0, 1, At, B1); PG8_BAR; PG8_SCHED;
	v_mfma_f32_16x16x32_bf16 v[60:63], v[128:131], v[170:173], v[60:63]
	v_mfma_f32_16x16x32_bf16 v[56:59], v[136:139], v[170:173], v[56:59]
	v_mfma_f32_16x16x32_bf16 v[44:47], v[128:131], v[178:181], v[44:47]
	v_mfma_f32_16x16x32_bf16 v[40:43], v[136:139], v[178:181], v[40:43]
	v_mfma_f32_16x16x32_bf16 v[28:31], v[128:131], v[194:197], v[28:31]
	v_mfma_f32_16x16x32_bf16 v[24:27], v[136:139], v[194:197], v[24:27]
	v_mfma_f32_16x16x32_bf16 v[12:15], v[128:131], v[202:205], v[12:15]
	v_mfma_f32_16x16x32_bf16 v[8:11], v[136:139], v[202:205], v[8:11]
	v_mfma_f32_16x16x32_bf16 v[60:63], v[132:135], v[174:177], v[60:63]
	v_mfma_f32_16x16x32_bf16 v[56:59], v[140:143], v[174:177], v[56:59]
	v_mfma_f32_16x16x32_bf16 v[44:47], v[132:135], v[186:189], v[44:47]
	v_mfma_f32_16x16x32_bf16 v[40:43], v[140:143], v[186:189], v[40:43]
	v_mfma_f32_16x16x32_bf16 v[28:31], v[132:135], v[198:201], v[28:31]
	v_mfma_f32_16x16x32_bf16 v[24:27], v[140:143], v[198:201], v[24:27]
	v_mfma_f32_16x16x32_bf16 v[12:15], v[132:135], v[206:209], v[12:15]
	v_mfma_f32_16x16x32_bf16 v[8:11], v[140:143], v[206:209], v[8:11]
	s_setprio 0
	s_setprio 1
	v_mfma_f32_16x16x32_bf16 v[52:55], v[144:147], v[170:173], v[52:55]
	v_mfma_f32_16x16x32_bf16 v[48:51], v[152:155], v[170:173], v[48:51]
	v_mfma_f32_16x16x32_bf16 v[36:39], v[144:147], v[178:181], v[36:39]
	v_mfma_f32_16x16x32_bf16 v[32:35], v[152:155], v[178:181], v[32:35]
	v_mfma_f32_16x16x32_bf16 v[20:23], v[144:147], v[194:197], v[20:23]
	v_mfma_f32_16x16x32_bf16 v[16:19], v[152:155], v[194:197], v[16:19]
	v_mfma_f32_16x16x32_bf16 v[4:7], v[144:147], v[202:205], v[4:7]
	v_mfma_f32_16x16x32_bf16 v[0:3], v[152:155], v[202:205], v[0:3]
	v_mfma_f32_16x16x32_bf16 v[52:55], v[148:151], v[174:177], v[52:55]
	v_mfma_f32_16x16x32_bf16 v[48:51], v[166:169], v[174:177], v[48:51]
	v_mfma_f32_16x16x32_bf16 v[36:39], v[148:151], v[186:189], v[36:39]
	v_mfma_f32_16x16x32_bf16 v[32:35], v[166:169], v[186:189], v[32:35]
	v_mfma_f32_16x16x32_bf16 v[20:23], v[148:151], v[198:201], v[20:23]
	v_mfma_f32_16x16x32_bf16 v[16:19], v[166:169], v[198:201], v[16:19]
	v_mfma_f32_16x16x32_bf16 v[4:7], v[148:151], v[206:209], v[4:7]
	v_mfma_f32_16x16x32_bf16 v[0:3], v[166:169], v[206:209], v[0:3]
	s_barrier
	s_setprio 0
	s_add_i32 s10, 0, 0x18000
	s_add_i32 s11, 0, 0x1c000
	v_add_u32_e32 v140, s10, v183
	v_add_u32_e32 v166, s11, v183
	ds_read_b128 v[128:131], v140
	ds_read_b128 v[132:135], v140 offset:1024
	ds_read_b128 v[136:139], v140 offset:2048
	ds_read_b128 v[140:143], v140 offset:3072
	ds_read_b128 v[144:147], v166
	ds_read_b128 v[148:151], v166 offset:1024
	ds_read_b128 v[152:155], v166 offset:2048
	ds_read_b128 v[166:169], v166 offset:3072
	s_add_u32 s46, s46, s52
	s_addc_u32 s47, s47, 0
	s_mov_b32 m0, s68
	v_lshl_add_u64 v[220:221], s[46:47], 0, v[156:157]
	ds_read_b128 v[170:173], v185 offset:32768
	ds_read_b128 v[174:177], v185 offset:33792
	ds_read_b128 v[178:181], v185 offset:34816
	ds_read_b128 v[186:189], v185 offset:35840
	ds_read_b128 v[194:197], v185 offset:36864
	ds_read_b128 v[198:201], v185 offset:37888
	ds_read_b128 v[202:205], v185 offset:38912
	ds_read_b128 v[206:209], v185 offset:39936
	global_load_lds_dwordx4 v[220:221], off
	v_lshl_add_u64 v[220:221], s[46:47], 0, v[158:159]
	s_mov_b32 m0, s69
	s_nop 0
	global_load_lds_dwordx4 v[220:221], off
	s_setprio 1
	s_waitcnt vmcnt(8)
	s_waitcnt lgkmcnt(0)
	s_barrier
	v_mfma_f32_16x16x32_bf16 v[124:127], v[128:131], v[170:173], v[124:127]
	v_mfma_f32_16x16x32_bf16 v[120:123], v[136:139], v[170:173], v[120:123]
	v_mfma_f32_16x16x32_bf16 v[108:111], v[128:131], v[178:181], v[108:111]
	v_mfma_f32_16x16x32_bf16 v[104:107], v[136:139], v[178:181], v[104:107]
	v_mfma_f32_16x16x32_bf16 v[92:95], v[128:131], v[194:197], v[92:95]
	v_mfma_f32_16x16x32_bf16 v[88:91], v[136:139], v[194:197], v[88:91]
	v_mfma_f32_16x16x32_bf16 v[76:79], v[128:131], v[202:205], v[76:79]
	v_mfma_f32_16x16x32_bf16 v[72:75], v[136:139], v[202:205], v[72:75]
	v_mfma_f32_16x16x32_bf16 v[124:127], v[132:135], v[174:177], v[124:127]
	v_mfma_f32_16x16x32_bf16 v[120:123], v[140:143], v[174:177], v[120:123]
	v_mfma_f32_16x16x32_bf16 v[108:111], v[132:135], v[186:189], v[108:111]
	v_mfma_f32_16x16x32_bf16 v[104:107], v[140:143], v[186:189], v[104:107]
	v_mfma_f32_16x16x32_bf16 v[92:95], v[132:135], v[198:201], v[92:95]
	v_mfma_f32_16x16x32_bf16 v[88:91], v[140:143], v[198:201], v[88:91]
	v_mfma_f32_16x16x32_bf16 v[76:79], v[132:135], v[206:209], v[76:79]
	v_mfma_f32_16x16x32_bf16 v[72:75], v[140:143], v[206:209], v[72:75]
	s_setprio 0
	s_setprio 1
	v_mfma_f32_16x16x32_bf16 v[116:119], v[144:147], v[170:173], v[116:119]
	v_mfma_f32_16x16x32_bf16 v[112:115], v[152:155], v[170:173], v[112:115]
	v_mfma_f32_16x16x32_bf16 v[100:103], v[144:147], v[178:181], v[100:103]
	v_mfma_f32_16x16x32_bf16 v[96:99], v[152:155], v[178:181], v[96:99]
	v_mfma_f32_16x16x32_bf16 v[84:87], v[144:147], v[194:197], v[84:87]
	v_mfma_f32_16x16x32_bf16 v[80:83], v[152:155], v[194:197], v[80:83]
	v_mfma_f32_16x16x32_bf16 v[68:71], v[144:147], v[202:205], v[68:71]
	v_mfma_f32_16x16x32_bf16 v[64:67], v[152:155], v[202:205], v[64:67]
	v_mfma_f32_16x16x32_bf16 v[116:119], v[148:151], v[174:177], v[116:119]
	v_mfma_f32_16x16x32_bf16 v[112:115], v[166:169], v[174:177], v[112:115]
	v_mfma_f32_16x16x32_bf16 v[100:103], v[148:151], v[186:189], v[100:103]
	v_mfma_f32_16x16x32_bf16 v[96:99], v[166:169], v[186:189], v[96:99]
	v_mfma_f32_16x16x32_bf16 v[84:87], v[148:151], v[198:201], v[84:87]
	v_mfma_f32_16x16x32_bf16 v[80:83], v[166:169], v[198:201], v[80:83]
	v_mfma_f32_16x16x32_bf16 v[68:71], v[148:151], v[206:209], v[68:71]
	v_mfma_f32_16x16x32_bf16 v[64:67], v[166:169], v[206:209], v[64:67]
	s_barrier
; #define PG8_STAGE(bufoff, gbase, voff) do { _Pragma("unroll") for (int _i = 0; _i < 2; ++_i) \
;         __builtin_amdgcn_global_load_lds((const unsigned*)((const char*)(gbase) + (voff)[_i]), (PG8_LAS unsigned*)(lds + (bufoff) + ldsw + _i * 8192), 16, 0, 0); } while (0)
; #define PG8_LDA(dst, b, h) do { _Pragma("unroll") for (int m = 0; m < 4; ++m) _Pragma("unroll") for (int k = 0; k < 2; ++k) dst[m][k] = *(const PG8_LAS bf16x8*)(lds + PG8_SA(b, h) + aoff + m * 2048 + k * 1024); } while (0)
; #define PG8_MMA(ai, bj, At, Bt) do { __builtin_amdgcn_s_setprio(1); _Pragma("unroll") for (int m = 0; m < 4; ++m) _Pragma("unroll") for (int n = 0; n < 2; ++n) _Pragma("unroll") for (int k = 0; k < 2; ++k) \
;         acc[ai][bj][m][n] = __builtin_amdgcn_mfma_f32_16x16x32_bf16(Bt[n][k], At[m][k], acc[ai][bj][m][n], 0, 0, 0); __builtin_amdgcn_s_setprio(0); } while (0)
; #define PG8_WAIT_V(n) asm volatile("s_waitcnt vmcnt(" #n ")" ::: "memory")
; #define PG8_WAIT_L(n) asm volatile("s_waitcnt lgkmcnt(" #n ")" ::: "memory")
; #define PG8_BAR __builtin_amdgcn_s_barrier()
; #define PG8_SCHED __builtin_amdgcn_sched_barrier(0)
; template <class Epi, class Sched, bool ALIGN_EPI = false, bool SP2 = false>
; __device__ __forceinline__ void gemm_phase(PG8_LAS unsigned char* lds, const Gemm g, const Sched& S, const Epi& E) {
;     ...
;             PG8_LDA(At, 1, 1); PG8_STAGE(PG8_SB(1, 0), b3, voffB); PG8_STAGE(PG8_SB(1, 1), b3 + hstep, voffB); PG8_STAGE(PG8_SA(1, 0), a3, voffA);
;             PG8_WAIT_V(8); PG8_WAIT_L(0); PG8_BAR; PG8_MMA(1, 0, At, B0); PG8_MMA(1, 1, At, B1); PG8_BAR; PG8_SCHED;
;     ...
;         if constexpr (ALIGN_EPI) { if (wr == 0) PG8_BAR; }
	s_setprio 0
	s_add_i32 s10, s10, s22
	v_lshl_add_u64 v[190:191], v[190:191], 0, s[36:37]
	s_mov_b32 m0, s10
	ds_read_b128 v[170:173], v185 offset:49152
	ds_read_b128 v[174:177], v185 offset:50176
	ds_read_b128 v[178:181], v185 offset:51200
	ds_read_b128 v[186:189], v185 offset:52224
	ds_read_b128 v[194:197], v185 offset:53248
	ds_read_b128 v[198:201], v185 offset:54272
	ds_read_b128 v[202:205], v185 offset:55296
	ds_read_b128 v[206:209], v185 offset:56320
	global_load_lds_dwordx4 v[190:191], off
	v_lshl_add_u64 v[190:191], v[210:211], 0, s[36:37]
	s_add_i32 m0, s10, 0x2000
	s_add_i32 s10, s11, s22
	global_load_lds_dwordx4 v[190:191], off
	v_lshl_add_u64 v[190:191], v[212:213], 0, s[36:37]
	s_mov_b32 m0, s10
	s_nop 0
	global_load_lds_dwordx4 v[190:191], off
	v_lshl_add_u64 v[190:191], v[214:215], 0, s[36:37]
	s_add_i32 m0, s10, 0x2000
	s_nop 0
	global_load_lds_dwordx4 v[190:191], off
	v_lshl_add_u64 v[190:191], v[216:217], 0, s[36:37]
	s_mov_b32 m0, s70
	s_nop 0
	global_load_lds_dwordx4 v[190:191], off
	v_lshl_add_u64 v[190:191], v[218:219], 0, s[36:37]
	s_mov_b32 m0, s71
	s_nop 0
	global_load_lds_dwordx4 v[190:191], off
	s_setprio 1
	s_waitcnt vmcnt(8)
	s_waitcnt lgkmcnt(0)
	s_barrier
	v_mfma_f32_16x16x32_bf16 v[60:63], v[128:131], v[170:173], v[60:63]
	v_mfma_f32_16x16x32_bf16 v[56:59], v[136:139], v[170:173], v[56:59]
	v_mfma_f32_16x16x32_bf16 v[44:47], v[128:131], v[178:181], v[44:47]
	v_mfma_f32_16x16x32_bf16 v[40:43], v[136:139], v[178:181], v[40:43]
	v_mfma_f32_16x16x32_bf16 v[28:31], v[128:131], v[194:197], v[28:31]
	v_mfma_f32_16x16x32_bf16 v[24:27], v[136:139], v[194:197], v[24:27]
	v_mfma_f32_16x16x32_bf16 v[12:15], v[128:131], v[202:205], v[12:15]
	v_mfma_f32_16x16x32_bf16 v[8:11], v[136:139], v[202:205], v[8:11]
	v_mfma_f32_16x16x32_bf16 v[60:63], v[132:135], v[174:177], v[60:63]
	v_mfma_f32_16x16x32_bf16 v[56:59], v[140:143], v[174:177], v[56:59]
	v_mfma_f32_16x16x32_bf16 v[44:47], v[132:135], v[186:189], v[44:47]
	v_mfma_f32_16x16x32_bf16 v[40:43], v[140:143], v[186:189], v[40:43]
	v_mfma_f32_16x16x32_bf16 v[28:31], v[132:135], v[198:201], v[28:31]
	v_mfma_f32_16x16x32_bf16 v[24:27], v[140:143], v[198:201], v[24:27]
	v_mfma_f32_16x16x32_bf16 v[12:15], v[132:135], v[206:209], v[12:15]
	v_mfma_f32_16x16x32_bf16 v[8:11], v[140:143], v[206:209], v[8:11]
	s_setprio 0
	s_setprio 1
	v_mfma_f32_16x16x32_bf16 v[52:55], v[144:147], v[170:173], v[52:55]
	v_mfma_f32_16x16x32_bf16 v[48:51], v[152:155], v[170:173], v[48:51]
	v_mfma_f32_16x16x32_bf16 v[36:39], v[144:147], v[178:181], v[36:39]
	v_mfma_f32_16x16x32_bf16 v[32:35], v[152:155], v[178:181], v[32:35]
	v_mfma_f32_16x16x32_bf16 v[20:23], v[144:147], v[194:197], v[20:23]
	v_mfma_f32_16x16x32_bf16 v[16:19], v[152:155], v[194:197], v[16:19]
	v_mfma_f32_16x16x32_bf16 v[4:7], v[144:147], v[202:205], v[4:7]
	v_mfma_f32_16x16x32_bf16 v[0:3], v[152:155], v[202:205], v[0:3]
	v_mfma_f32_16x16x32_bf16 v[52:55], v[148:151], v[174:177], v[52:55]
	v_mfma_f32_16x16x32_bf16 v[48:51], v[166:169], v[174:177], v[48:51]
	v_mfma_f32_16x16x32_bf16 v[36:39], v[148:151], v[186:189], v[36:39]
	v_mfma_f32_16x16x32_bf16 v[32:35], v[166:169], v[186:189], v[32:35]
	v_mfma_f32_16x16x32_bf16 v[20:23], v[148:151], v[198:201], v[20:23]
	v_mfma_f32_16x16x32_bf16 v[16:19], v[166:169], v[198:201], v[16:19]
	v_mfma_f32_16x16x32_bf16 v[4:7], v[148:151], v[206:209], v[4:7]
	v_mfma_f32_16x16x32_bf16 v[0:3], v[166:169], v[206:209], v[0:3]
	s_barrier
	s_setprio 0
	s_add_u32 s44, s44, 0x100
	s_addc_u32 s45, s45, 0
	s_add_u32 s19, s19, 0x100
	s_addc_u32 s20, s20, 0
	s_cmp_ge_u32 s66, s73
	s_mov_b32 s46, s66
	s_cbranch_scc0 .LBB0_63
	s_and_b64 vcc, exec, s[56:57]
	s_cbranch_vccz .LBB0_66
	s_barrier

; #define PG8_STAGE(bufoff, gbase, voff) do { _Pragma("unroll") for (int _i = 0; _i < 2; ++_i) \
;         __builtin_amdgcn_global_load_lds((const unsigned*)((const char*)(gbase) + (voff)[_i]), (PG8_LAS unsigned*)(lds + (bufoff) + ldsw + _i * 8192), 16, 0, 0); } while (0)
; #define PG8_LDA(dst, b, h) do { _Pragma("unroll") for (int m = 0; m < 4; ++m) _Pragma("unroll") for (int k = 0; k < 2; ++k) dst[m][k] = *(const PG8_LAS bf16x8*)(lds + PG8_SA(b, h) + aoff + m * 2048 + k * 1024); } while (0)
; #define PG8_LDB(dst, b, h) do { _Pragma("unroll") for (int n = 0; n < 2; ++n) _Pragma("unroll") for (int k = 0; k < 2; ++k) dst[n][k] = *(const PG8_LAS bf16x8*)(lds + PG8_SB(b, h) + boff + n * 2048 + k * 1024); } while (0)
; #define PG8_MMA(ai, bj, At, Bt) do { __builtin_amdgcn_s_setprio(1); _Pragma("unroll") for (int m = 0; m < 4; ++m) _Pragma("unroll") for (int n = 0; n < 2; ++n) _Pragma("unroll") for (int k = 0; k < 2; ++k) \
;         acc[ai][bj][m][n] = __builtin_amdgcn_mfma_f32_16x16x32_bf16(Bt[n][k], At[m][k], acc[ai][bj][m][n], 0, 0, 0); __builtin_amdgcn_s_setprio(0); } while (0)
; #define PG8_WAIT_V(n) asm volatile("s_waitcnt vmcnt(" #n ")" ::: "memory")
; #define PG8_WAIT_L(n) asm volatile("s_waitcnt lgkmcnt(" #n ")" ::: "memory")
; template <class Epi, class Sched, bool ALIGN_EPI = false, bool SP2 = false>
; __device__ __forceinline__ void gemm_phase(PG8_LAS unsigned char* lds, const Gemm g, const Sched& S, const Epi& E) {
;     ...
;             const bool last = (t == nt - 2);
;             const char* a1 = cA + (size_t)(t + 1) * kstep;
;             const char* a2 = last ? nA : cA + (size_t)(t + 2) * kstep; const char* b2 = last ? nB : cB + (size_t)(t + 2) * kstep;
;             const char* a3 = a2 + kstep; const char* b3 = b2 + kstep;
;             if (last && has_next) S.a_ready(nxt);
;             if constexpr (SP2) {
;             PG8_LDB(B0, 0, 0); PG8_LDB(B1, 0, 1); PG8_SCHED; PG8_LDA(At, 0, 0); PG8_STAGE(PG8_SA(1, 1), a1 + hstep, voffA);
;             PG8_WAIT_V(8); PG8_WAIT_L(0); PG8_BAR; PG8_MMA(0, 0, At, B0); PG8_MMA(0, 1, At, B1); PG8_BAR; PG8_SCHED;
;             PG8_LDA(At, 0, 1); PG8_STAGE(PG8_SB(0, 0), b2, voffB); PG8_STAGE(PG8_SB(0, 1), b2 + hstep, voffB); PG8_STAGE(PG8_SA(0, 0), a2, voffA);
;             PG8_WAIT_V(8); PG8_WAIT_L(0); PG8_BAR; PG8_MMA(1, 0, At, B0); PG8_MMA(1, 1, At, B1); PG8_BAR; PG8_SCHED;
.LBB0_200:
	s_add_u32 s10, s56, 0xfffc0080
	s_addc_u32 s11, s57, -1
	s_add_i32 s77, 0, 0x10000
	s_cmp_eq_u32 s76, 12
	s_cselect_b32 s61, s18, s11
	s_cselect_b32 s60, s19, s10
	s_cselect_b32 s59, s20, s51
	s_cselect_b32 s58, s43, s49
	s_add_i32 s10, 0, 0x14000
	v_add_u32_e32 v140, s77, v163
	v_add_u32_e32 v162, s10, v163
	ds_read_b128 v[128:131], v140
	ds_read_b128 v[132:135], v140 offset:1024
	ds_read_b128 v[136:139], v140 offset:2048
	ds_read_b128 v[140:143], v140 offset:3072
	ds_read_b128 v[166:169], v162
	ds_read_b128 v[170:173], v162 offset:1024
	ds_read_b128 v[174:177], v162 offset:2048
	ds_read_b128 v[178:181], v162 offset:3072
	v_lshl_add_u64 v[190:191], s[56:57], 0, v[158:159]
	s_add_i32 m0, s64, 0xc000
	ds_read_b128 v[182:185], v165
	ds_read_b128 v[186:189], v165 offset:1024
	ds_read_b128 v[194:197], v165 offset:2048
	ds_read_b128 v[198:201], v165 offset:3072
	ds_read_b128 v[202:205], v165 offset:4096
	ds_read_b128 v[206:209], v165 offset:5120
	ds_read_b128 v[210:213], v165 offset:6144
	ds_read_b128 v[214:217], v165 offset:7168
	global_load_lds_dwordx4 v[190:191], off
	v_lshl_add_u64 v[190:191], s[56:57], 0, v[160:161]
	s_add_i32 m0, s64, 0xe000
	s_nop 0
	global_load_lds_dwordx4 v[190:191], off
	s_setprio 1
	s_waitcnt vmcnt(8)
	s_waitcnt lgkmcnt(0)
	s_barrier
	v_mfma_f32_16x16x32_bf16 v[124:127], v[128:131], v[182:185], v[124:127]
	v_mfma_f32_16x16x32_bf16 v[120:123], v[136:139], v[182:185], v[120:123]
	v_mfma_f32_16x16x32_bf16 v[112:115], v[128:131], v[194:197], v[112:115]
	v_mfma_f32_16x16x32_bf16 v[104:107], v[136:139], v[194:197], v[104:107]
	v_mfma_f32_16x16x32_bf16 v[96:99], v[128:131], v[202:205], v[96:99]
	v_mfma_f32_16x16x32_bf16 v[88:91], v[136:139], v[202:205], v[88:91]
	v_mfma_f32_16x16x32_bf16 v[80:83], v[128:131], v[210:213], v[80:83]
	v_mfma_f32_16x16x32_bf16 v[72:75], v[136:139], v[210:213], v[72:75]
	v_mfma_f32_16x16x32_bf16 v[124:127], v[132:135], v[186:189], v[124:127]
	v_mfma_f32_16x16x32_bf16 v[120:123], v[140:143], v[186:189], v[120:123]
	v_mfma_f32_16x16x32_bf16 v[112:115], v[132:135], v[198:201], v[112:115]
	v_mfma_f32_16x16x32_bf16 v[104:107], v[140:143], v[198:201], v[104:107]
	v_mfma_f32_16x16x32_bf16 v[96:99], v[132:135], v[206:209], v[96:99]
	v_mfma_f32_16x16x32_bf16 v[88:91], v[140:143], v[206:209], v[88:91]
	v_mfma_f32_16x16x32_bf16 v[80:83], v[132:135], v[214:217], v[80:83]
	v_mfma_f32_16x16x32_bf16 v[72:75], v[140:143], v[214:217], v[72:75]
	s_setprio 0
	s_setprio 1
	v_mfma_f32_16x16x32_bf16 v[116:119], v[166:169], v[182:185], v[116:119]
	v_mfma_f32_16x16x32_bf16 v[108:111], v[174:177], v[182:185], v[108:111]
	v_mfma_f32_16x16x32_bf16 v[100:103], v[166:169], v[194:197], v[100:103]
	v_mfma_f32_16x16x32_bf16 v[92:95], v[174:177], v[194:197], v[92:95]
	v_mfma_f32_16x16x32_bf16 v[84:87], v[166:169], v[202:205], v[84:87]
	v_mfma_f32_16x16x32_bf16 v[76:79], v[174:177], v[202:205], v[76:79]
	v_mfma_f32_16x16x32_bf16 v[68:71], v[166:169], v[210:213], v[68:71]
	v_mfma_f32_16x16x32_bf16 v[64:67], v[174:177], v[210:213], v[64:67]
	v_mfma_f32_16x16x32_bf16 v[116:119], v[170:173], v[186:189], v[116:119]
	v_mfma_f32_16x16x32_bf16 v[108:111], v[178:181], v[186:189], v[108:111]
	v_mfma_f32_16x16x32_bf16 v[100:103], v[170:173], v[198:201], v[100:103]
	v_mfma_f32_16x16x32_bf16 v[92:95], v[178:181], v[198:201], v[92:95]
	v_mfma_f32_16x16x32_bf16 v[84:87], v[170:173], v[206:209], v[84:87]
	v_mfma_f32_16x16x32_bf16 v[76:79], v[178:181], v[206:209], v[76:79]
	v_mfma_f32_16x16x32_bf16 v[68:71], v[170:173], v[214:217], v[68:71]
	v_mfma_f32_16x16x32_bf16 v[64:67], v[178:181], v[214:217], v[64:67]
	s_barrier
	s_setprio 0
	s_add_i32 s11, s77, s63
	v_lshl_add_u64 v[190:191], s[58:59], 0, v[146:147]
	s_mov_b32 m0, s11
	ds_read_b128 v[182:185], v165 offset:16384
	ds_read_b128 v[186:189], v165 offset:17408
	ds_read_b128 v[194:197], v165 offset:18432
	ds_read_b128 v[198:201], v165 offset:19456
	ds_read_b128 v[202:205], v165 offset:20480
	ds_read_b128 v[206:209], v165 offset:21504
	ds_read_b128 v[210:213], v165 offset:22528
	ds_read_b128 v[214:217], v165 offset:23552
	global_load_lds_dwordx4 v[190:191], off
	s_add_i32 m0, s11, 0x2000
	s_add_u32 s78, s58, 0x40000
	v_lshl_add_u64 v[218:219], s[58:59], 0, v[150:151]
	s_addc_u32 s79, s59, 0
	s_add_i32 s10, s10, s63
	global_load_lds_dwordx4 v[218:219], off
	v_lshl_add_u64 v[220:221], s[78:79], 0, v[146:147]
	s_mov_b32 m0, s10
	v_lshl_add_u64 v[222:223], s[60:61], 0, v[148:149]
	global_load_lds_dwordx4 v[220:221], off
	v_lshl_add_u64 v[220:221], s[78:79], 0, v[150:151]
	s_add_i32 m0, s10, 0x2000
	s_nop 0
	global_load_lds_dwordx4 v[220:221], off
	v_lshl_add_u64 v[220:221], s[60:61], 0, v[144:145]
	s_mov_b32 m0, s64
	s_nop 0
	global_load_lds_dwordx4 v[220:221], off
	s_mov_b32 m0, s65
	s_nop 0
	global_load_lds_dwordx4 v[222:223], off
	s_setprio 1
	s_waitcnt vmcnt(8)
	s_waitcnt lgkmcnt(0)
	s_barrier
; #define PG8_STAGE(bufoff, gbase, voff) do { _Pragma("unroll") for (int _i = 0; _i < 2; ++_i) \
;         __builtin_amdgcn_global_load_lds((const unsigned*)((const char*)(gbase) + (voff)[_i]), (PG8_LAS unsigned*)(lds + (bufoff) + ldsw + _i * 8192), 16, 0, 0); } while (0)
; #define PG8_LDA(dst, b, h) do { _Pragma("unroll") for (int m = 0; m < 4; ++m) _Pragma("unroll") for (int k = 0; k < 2; ++k) dst[m][k] = *(const PG8_LAS bf16x8*)(lds + PG8_SA(b, h) + aoff + m * 2048 + k * 1024); } while (0)
; #define PG8_LDB(dst, b, h) do { _Pragma("unroll") for (int n = 0; n < 2; ++n) _Pragma("unroll") for (int k = 0; k < 2; ++k) dst[n][k] = *(const PG8_LAS bf16x8*)(lds + PG8_SB(b, h) + boff + n * 2048 + k * 1024); } while (0)
; #define PG8_MMA(ai, bj, At, Bt) do { __builtin_amdgcn_s_setprio(1); _Pragma("unroll") for (int m = 0; m < 4; ++m) _Pragma("unroll") for (int n = 0; n < 2; ++n) _Pragma("unroll") for (int k = 0; k < 2; ++k) \
;         acc[ai][bj][m][n] = __builtin_amdgcn_mfma_f32_16x16x32_bf16(Bt[n][k], At[m][k], acc[ai][bj][m][n], 0, 0, 0); __builtin_amdgcn_s_setprio(0); } while (0)
; #define PG8_WAIT_V(n) asm volatile("s_waitcnt vmcnt(" #n ")" ::: "memory")
; #define PG8_WAIT_L(n) asm volatile("s_waitcnt lgkmcnt(" #n ")" ::: "memory")
; #define PG8_BAR __builtin_amdgcn_s_barrier()
; #define PG8_SCHED __builtin_amdgcn_sched_barrier(0)
; template <class Epi, class Sched, bool ALIGN_EPI = false, bool SP2 = false>
; __device__ __forceinline__ void gemm_phase(PG8_LAS unsigned char* lds, const Gemm g, const Sched& S, const Epi& E) {
;     ...
;             PG8_WAIT_V(8); PG8_WAIT_L(0); PG8_BAR; PG8_MMA(1, 0, At, B0); PG8_MMA(1, 1, At, B1); PG8_BAR; PG8_SCHED;
;             PG8_LDB(B0, 1, 0); PG8_LDB(B1, 1, 1); PG8_SCHED; PG8_LDA(At, 1, 0); PG8_STAGE(PG8_SA(0, 1), a2 + hstep, voffA);
;             PG8_WAIT_V(8); PG8_WAIT_L(0); PG8_BAR; PG8_MMA(0, 0, At, B0); PG8_MMA(0, 1, At, B1); PG8_BAR; PG8_SCHED;
	v_mfma_f32_16x16x32_bf16 v[60:63], v[128:131], v[182:185], v[60:63]
	v_mfma_f32_16x16x32_bf16 v[56:59], v[136:139], v[182:185], v[56:59]
	v_mfma_f32_16x16x32_bf16 v[48:51], v[128:131], v[194:197], v[48:51]
	v_mfma_f32_16x16x32_bf16 v[40:43], v[136:139], v[194:197], v[40:43]
	v_mfma_f32_16x16x32_bf16 v[32:35], v[128:131], v[202:205], v[32:35]
	v_mfma_f32_16x16x32_bf16 v[24:27], v[136:139], v[202:205], v[24:27]
	v_mfma_f32_16x16x32_bf16 v[16:19], v[128:131], v[210:213], v[16:19]
	v_mfma_f32_16x16x32_bf16 v[8:11], v[136:139], v[210:213], v[8:11]
	v_mfma_f32_16x16x32_bf16 v[60:63], v[132:135], v[186:189], v[60:63]
	v_mfma_f32_16x16x32_bf16 v[56:59], v[140:143], v[186:189], v[56:59]
	v_mfma_f32_16x16x32_bf16 v[48:51], v[132:135], v[198:201], v[48:51]
	v_mfma_f32_16x16x32_bf16 v[40:43], v[140:143], v[198:201], v[40:43]
	v_mfma_f32_16x16x32_bf16 v[32:35], v[132:135], v[206:209], v[32:35]
	v_mfma_f32_16x16x32_bf16 v[24:27], v[140:143], v[206:209], v[24:27]
	v_mfma_f32_16x16x32_bf16 v[16:19], v[132:135], v[214:217], v[16:19]
	v_mfma_f32_16x16x32_bf16 v[8:11], v[140:143], v[214:217], v[8:11]
	s_setprio 0
	s_setprio 1
	v_mfma_f32_16x16x32_bf16 v[52:55], v[166:169], v[182:185], v[52:55]
	v_mfma_f32_16x16x32_bf16 v[44:47], v[174:177], v[182:185], v[44:47]
	v_mfma_f32_16x16x32_bf16 v[36:39], v[166:169], v[194:197], v[36:39]
	v_mfma_f32_16x16x32_bf16 v[28:31], v[174:177], v[194:197], v[28:31]
	v_mfma_f32_16x16x32_bf16 v[20:23], v[166:169], v[202:205], v[20:23]
	v_mfma_f32_16x16x32_bf16 v[12:15], v[174:177], v[202:205], v[12:15]
	v_mfma_f32_16x16x32_bf16 v[4:7], v[166:169], v[210:213], v[4:7]
	v_mfma_f32_16x16x32_bf16 v[0:3], v[174:177], v[210:213], v[0:3]
	v_mfma_f32_16x16x32_bf16 v[52:55], v[170:173], v[186:189], v[52:55]
	v_mfma_f32_16x16x32_bf16 v[44:47], v[178:181], v[186:189], v[44:47]
	v_mfma_f32_16x16x32_bf16 v[36:39], v[170:173], v[198:201], v[36:39]
	v_mfma_f32_16x16x32_bf16 v[28:31], v[178:181], v[198:201], v[28:31]
	v_mfma_f32_16x16x32_bf16 v[20:23], v[170:173], v[206:209], v[20:23]
	v_mfma_f32_16x16x32_bf16 v[12:15], v[178:181], v[206:209], v[12:15]
	v_mfma_f32_16x16x32_bf16 v[4:7], v[170:173], v[214:217], v[4:7]
	v_mfma_f32_16x16x32_bf16 v[0:3], v[178:181], v[214:217], v[0:3]
	s_barrier
	s_setprio 0
	s_add_i32 s10, 0, 0x18000
	s_add_i32 s11, 0, 0x1c000
	v_add_u32_e32 v140, s10, v163
	v_add_u32_e32 v162, s11, v163
	ds_read_b128 v[128:131], v140
	ds_read_b128 v[132:135], v140 offset:1024
	ds_read_b128 v[136:139], v140 offset:2048
	ds_read_b128 v[140:143], v140 offset:3072
	ds_read_b128 v[166:169], v162
	ds_read_b128 v[170:173], v162 offset:1024
	ds_read_b128 v[174:177], v162 offset:2048
	ds_read_b128 v[178:181], v162 offset:3072
	s_add_u32 s60, s60, 0x40000
	s_addc_u32 s61, s61, 0
	s_mov_b32 m0, s66
	v_lshl_add_u64 v[224:225], s[60:61], 0, v[144:145]
	ds_read_b128 v[182:185], v165 offset:32768
	ds_read_b128 v[186:189], v165 offset:33792
	ds_read_b128 v[194:197], v165 offset:34816
	ds_read_b128 v[198:201], v165 offset:35840
	ds_read_b128 v[202:205], v165 offset:36864
	ds_read_b128 v[206:209], v165 offset:37888
	ds_read_b128 v[210:213], v165 offset:38912
	ds_read_b128 v[214:217], v165 offset:39936
	global_load_lds_dwordx4 v[224:225], off
	v_lshl_add_u64 v[224:225], s[60:61], 0, v[148:149]
	s_mov_b32 m0, s67
	s_nop 0
	global_load_lds_dwordx4 v[224:225], off
	s_setprio 1
	s_waitcnt vmcnt(8)
	s_waitcnt lgkmcnt(0)
	s_barrier
	v_mfma_f32_16x16x32_bf16 v[124:127], v[128:131], v[182:185], v[124:127]
	v_mfma_f32_16x16x32_bf16 v[120:123], v[136:139], v[182:185], v[120:123]
	v_mfma_f32_16x16x32_bf16 v[112:115], v[128:131], v[194:197], v[112:115]
	v_mfma_f32_16x16x32_bf16 v[104:107], v[136:139], v[194:197], v[104:107]
	v_mfma_f32_16x16x32_bf16 v[96:99], v[128:131], v[202:205], v[96:99]
	v_mfma_f32_16x16x32_bf16 v[88:91], v[136:139], v[202:205], v[88:91]
	v_mfma_f32_16x16x32_bf16 v[80:83], v[128:131], v[210:213], v[80:83]
	v_mfma_f32_16x16x32_bf16 v[72:75], v[136:139], v[210:213], v[72:75]
	v_mfma_f32_16x16x32_bf16 v[124:127], v[132:135], v[186:189], v[124:127]
	v_mfma_f32_16x16x32_bf16 v[120:123], v[140:143], v[186:189], v[120:123]
	v_mfma_f32_16x16x32_bf16 v[112:115], v[132:135], v[198:201], v[112:115]
	v_mfma_f32_16x16x32_bf16 v[104:107], v[140:143], v[198:201], v[104:107]
	v_mfma_f32_16x16x32_bf16 v[96:99], v[132:135], v[206:209], v[96:99]
	v_mfma_f32_16x16x32_bf16 v[88:91], v[140:143], v[206:209], v[88:91]
	v_mfma_f32_16x16x32_bf16 v[80:83], v[132:135], v[214:217], v[80:83]
	v_mfma_f32_16x16x32_bf16 v[72:75], v[140:143], v[214:217], v[72:75]
	s_setprio 0
	s_setprio 1
	v_mfma_f32_16x16x32_bf16 v[116:119], v[166:169], v[182:185], v[116:119]
	v_mfma_f32_16x16x32_bf16 v[108:111], v[174:177], v[182:185], v[108:111]
	v_mfma_f32_16x16x32_bf16 v[100:103], v[166:169], v[194:197], v[100:103]
	v_mfma_f32_16x16x32_bf16 v[92:95], v[174:177], v[194:197], v[92:95]
	v_mfma_f32_16x16x32_bf16 v[84:87], v[166:169], v[202:205], v[84:87]
	v_mfma_f32_16x16x32_bf16 v[76:79], v[174:177], v[202:205], v[76:79]
	v_mfma_f32_16x16x32_bf16 v[68:71], v[166:169], v[210:213], v[68:71]
	v_mfma_f32_16x16x32_bf16 v[64:67], v[174:177], v[210:213], v[64:67]
	v_mfma_f32_16x16x32_bf16 v[116:119], v[170:173], v[186:189], v[116:119]
	v_mfma_f32_16x16x32_bf16 v[108:111], v[178:181], v[186:189], v[108:111]
	v_mfma_f32_16x16x32_bf16 v[100:103], v[170:173], v[198:201], v[100:103]
	v_mfma_f32_16x16x32_bf16 v[92:95], v[178:181], v[198:201], v[92:95]
	v_mfma_f32_16x16x32_bf16 v[84:87], v[170:173], v[206:209], v[84:87]
	v_mfma_f32_16x16x32_bf16 v[76:79], v[178:181], v[206:209], v[76:79]
	v_mfma_f32_16x16x32_bf16 v[68:71], v[170:173], v[214:217], v[68:71]
	v_mfma_f32_16x16x32_bf16 v[64:67], v[178:181], v[214:217], v[64:67]
	s_barrier
; #define PG8_STAGE(bufoff, gbase, voff) do { _Pragma("unroll") for (int _i = 0; _i < 2; ++_i) \
;         __builtin_amdgcn_global_load_lds((const unsigned*)((const char*)(gbase) + (voff)[_i]), (PG8_LAS unsigned*)(lds + (bufoff) + ldsw + _i * 8192), 16, 0, 0); } while (0)
; #define PG8_LDA(dst, b, h) do { _Pragma("unroll") for (int m = 0; m < 4; ++m) _Pragma("unroll") for (int k = 0; k < 2; ++k) dst[m][k] = *(const PG8_LAS bf16x8*)(lds + PG8_SA(b, h) + aoff + m * 2048 + k * 1024); } while (0)
; #define PG8_MMA(ai, bj, At, Bt) do { __builtin_amdgcn_s_setprio(1); _Pragma("unroll") for (int m = 0; m < 4; ++m) _Pragma("unroll") for (int n = 0; n < 2; ++n) _Pragma("unroll") for (int k = 0; k < 2; ++k) \
;         acc[ai][bj][m][n] = __builtin_amdgcn_mfma_f32_16x16x32_bf16(Bt[n][k], At[m][k], acc[ai][bj][m][n], 0, 0, 0); __builtin_amdgcn_s_setprio(0); } while (0)
; #define PG8_WAIT_V(n) asm volatile("s_waitcnt vmcnt(" #n ")" ::: "memory")
; #define PG8_WAIT_L(n) asm volatile("s_waitcnt lgkmcnt(" #n ")" ::: "memory")
; #define PG8_BAR __builtin_amdgcn_s_barrier()
; #define PG8_SCHED __builtin_amdgcn_sched_barrier(0)
; template <class Epi, class Sched, bool ALIGN_EPI = false, bool SP2 = false>
; __device__ __forceinline__ void gemm_phase(PG8_LAS unsigned char* lds, const Gemm g, const Sched& S, const Epi& E) {
;     ...
;             PG8_LDA(At, 1, 1); PG8_STAGE(PG8_SB(1, 0), b3, voffB); PG8_STAGE(PG8_SB(1, 1), b3 + hstep, voffB); PG8_STAGE(PG8_SA(1, 0), a3, voffA);
;             PG8_WAIT_V(8); PG8_WAIT_L(0); PG8_BAR; PG8_MMA(1, 0, At, B0); PG8_MMA(1, 1, At, B1); PG8_BAR; PG8_SCHED;
;     ...
;         if constexpr (ALIGN_EPI) { if (wr == 0) PG8_BAR; }
	s_setprio 0
	s_add_i32 s10, s10, s63
	v_lshl_add_u64 v[190:191], v[190:191], 0, s[36:37]
	s_mov_b32 m0, s10
	ds_read_b128 v[182:185], v165 offset:49152
	ds_read_b128 v[186:189], v165 offset:50176
	ds_read_b128 v[194:197], v165 offset:51200
	ds_read_b128 v[198:201], v165 offset:52224
	ds_read_b128 v[202:205], v165 offset:53248
	ds_read_b128 v[206:209], v165 offset:54272
	ds_read_b128 v[210:213], v165 offset:55296
	ds_read_b128 v[214:217], v165 offset:56320
	global_load_lds_dwordx4 v[190:191], off
	s_add_i32 m0, s10, 0x2000
	s_add_u32 s58, s58, 0x40080
	v_lshl_add_u64 v[190:191], v[218:219], 0, s[36:37]
	s_addc_u32 s59, s59, 0
	s_add_i32 s10, s11, s63
	global_load_lds_dwordx4 v[190:191], off
	v_lshl_add_u64 v[190:191], s[58:59], 0, v[146:147]
	s_mov_b32 m0, s10
	s_nop 0
	global_load_lds_dwordx4 v[190:191], off
	v_lshl_add_u64 v[190:191], s[58:59], 0, v[150:151]
	s_add_i32 m0, s10, 0x2000
	s_nop 0
	global_load_lds_dwordx4 v[190:191], off
	v_lshl_add_u64 v[190:191], v[220:221], 0, s[36:37]
	s_mov_b32 m0, s70
	s_nop 0
	global_load_lds_dwordx4 v[190:191], off
	v_lshl_add_u64 v[190:191], v[222:223], 0, s[36:37]
	s_mov_b32 m0, s71
	s_nop 0
	global_load_lds_dwordx4 v[190:191], off
	s_setprio 1
	s_waitcnt vmcnt(8)
	s_waitcnt lgkmcnt(0)
	s_barrier
	v_mfma_f32_16x16x32_bf16 v[60:63], v[128:131], v[182:185], v[60:63]
	v_mfma_f32_16x16x32_bf16 v[56:59], v[136:139], v[182:185], v[56:59]
	v_mfma_f32_16x16x32_bf16 v[48:51], v[128:131], v[194:197], v[48:51]
	v_mfma_f32_16x16x32_bf16 v[40:43], v[136:139], v[194:197], v[40:43]
	v_mfma_f32_16x16x32_bf16 v[32:35], v[128:131], v[202:205], v[32:35]
	v_mfma_f32_16x16x32_bf16 v[24:27], v[136:139], v[202:205], v[24:27]
	v_mfma_f32_16x16x32_bf16 v[16:19], v[128:131], v[210:213], v[16:19]
	v_mfma_f32_16x16x32_bf16 v[8:11], v[136:139], v[210:213], v[8:11]
	v_mfma_f32_16x16x32_bf16 v[60:63], v[132:135], v[186:189], v[60:63]
	v_mfma_f32_16x16x32_bf16 v[56:59], v[140:143], v[186:189], v[56:59]
	v_mfma_f32_16x16x32_bf16 v[48:51], v[132:135], v[198:201], v[48:51]
	v_mfma_f32_16x16x32_bf16 v[40:43], v[140:143], v[198:201], v[40:43]
	v_mfma_f32_16x16x32_bf16 v[32:35], v[132:135], v[206:209], v[32:35]
	v_mfma_f32_16x16x32_bf16 v[24:27], v[140:143], v[206:209], v[24:27]
	v_mfma_f32_16x16x32_bf16 v[16:19], v[132:135], v[214:217], v[16:19]
	v_mfma_f32_16x16x32_bf16 v[8:11], v[140:143], v[214:217], v[8:11]
	s_setprio 0
	s_setprio 1
	v_mfma_f32_16x16x32_bf16 v[52:55], v[166:169], v[182:185], v[52:55]
	v_mfma_f32_16x16x32_bf16 v[44:47], v[174:177], v[182:185], v[44:47]
	v_mfma_f32_16x16x32_bf16 v[36:39], v[166:169], v[194:197], v[36:39]
	v_mfma_f32_16x16x32_bf16 v[28:31], v[174:177], v[194:197], v[28:31]
	v_mfma_f32_16x16x32_bf16 v[20:23], v[166:169], v[202:205], v[20:23]
	v_mfma_f32_16x16x32_bf16 v[12:15], v[174:177], v[202:205], v[12:15]
	v_mfma_f32_16x16x32_bf16 v[4:7], v[166:169], v[210:213], v[4:7]
	v_mfma_f32_16x16x32_bf16 v[0:3], v[174:177], v[210:213], v[0:3]
	v_mfma_f32_16x16x32_bf16 v[52:55], v[170:173], v[186:189], v[52:55]
	v_mfma_f32_16x16x32_bf16 v[44:47], v[178:181], v[186:189], v[44:47]
	v_mfma_f32_16x16x32_bf16 v[36:39], v[170:173], v[198:201], v[36:39]
	v_mfma_f32_16x16x32_bf16 v[28:31], v[178:181], v[198:201], v[28:31]
	v_mfma_f32_16x16x32_bf16 v[20:23], v[170:173], v[206:209], v[20:23]
	v_mfma_f32_16x16x32_bf16 v[12:15], v[178:181], v[206:209], v[12:15]
	v_mfma_f32_16x16x32_bf16 v[4:7], v[170:173], v[214:217], v[4:7]
	v_mfma_f32_16x16x32_bf16 v[0:3], v[178:181], v[214:217], v[0:3]
	s_barrier
	s_setprio 0
	s_add_i32 s76, s76, 2
	s_add_u32 s56, s56, 0x100
	s_addc_u32 s57, s57, 0
	s_add_u32 s49, s49, 0x100
	s_addc_u32 s51, s51, 0
	s_cmp_gt_u32 s76, 13
	s_cbranch_scc0 .LBB0_200
	s_and_b64 vcc, exec, s[44:45]
	s_cbranch_vccz .LBB0_203
	s_barrier

; #define PG8_STAGE(bufoff, gbase, voff) do { _Pragma("unroll") for (int _i = 0; _i < 2; ++_i) \
;         __builtin_amdgcn_global_load_lds((const unsigned*)((const char*)(gbase) + (voff)[_i]), (PG8_LAS unsigned*)(lds + (bufoff) + ldsw + _i * 8192), 16, 0, 0); } while (0)
; #define PG8_LDA(dst, b, h) do { _Pragma("unroll") for (int m = 0; m < 4; ++m) _Pragma("unroll") for (int k = 0; k < 2; ++k) dst[m][k] = *(const PG8_LAS bf16x8*)(lds + PG8_SA(b, h) + aoff + m * 2048 + k * 1024); } while (0)
; #define PG8_LDB(dst, b, h) do { _Pragma("unroll") for (int n = 0; n < 2; ++n) _Pragma("unroll") for (int k = 0; k < 2; ++k) dst[n][k] = *(const PG8_LAS bf16x8*)(lds + PG8_SB(b, h) + boff + n * 2048 + k * 1024); } while (0)
; #define PG8_MMA(ai, bj, At, Bt) do { __builtin_amdgcn_s_setprio(1); _Pragma("unroll") for (int m = 0; m < 4; ++m) _Pragma("unroll") for (int n = 0; n < 2; ++n) _Pragma("unroll") for (int k = 0; k < 2; ++k) \
;         acc[ai][bj][m][n] = __builtin_amdgcn_mfma_f32_16x16x32_bf16(Bt[n][k], At[m][k], acc[ai][bj][m][n], 0, 0, 0); __builtin_amdgcn_s_setprio(0); } while (0)
; #define PG8_WAIT_V(n) asm volatile("s_waitcnt vmcnt(" #n ")" ::: "memory")
; #define PG8_WAIT_L(n) asm volatile("s_waitcnt lgkmcnt(" #n ")" ::: "memory")
; template <class Epi, class Sched, bool ALIGN_EPI = false, bool SP2 = false>
; __device__ __forceinline__ void gemm_phase(PG8_LAS unsigned char* lds, const Gemm g, const Sched& S, const Epi& E) {
;     ...
;             const bool last = (t == nt - 2);
;             const char* a1 = cA + (size_t)(t + 1) * kstep;
;             const char* a2 = last ? nA : cA + (size_t)(t + 2) * kstep; const char* b2 = last ? nB : cB + (size_t)(t + 2) * kstep;
;             const char* a3 = a2 + kstep; const char* b3 = b2 + kstep;
;             if (last && has_next) S.a_ready(nxt);
;             if constexpr (SP2) {
;             PG8_LDB(B0, 0, 0); PG8_LDB(B1, 0, 1); PG8_SCHED; PG8_LDA(At, 0, 0); PG8_STAGE(PG8_SA(1, 1), a1 + hstep, voffA);
;             PG8_WAIT_V(8); PG8_WAIT_L(0); PG8_BAR; PG8_MMA(0, 0, At, B0); PG8_MMA(0, 1, At, B1); PG8_BAR; PG8_SCHED;
;             PG8_LDA(At, 0, 1); PG8_STAGE(PG8_SB(0, 0), b2, voffB); PG8_STAGE(PG8_SB(0, 1), b2 + hstep, voffB); PG8_STAGE(PG8_SA(0, 0), a2, voffA);
;             PG8_WAIT_V(8); PG8_WAIT_L(0); PG8_BAR; PG8_MMA(1, 0, At, B0); PG8_MMA(1, 1, At, B1); PG8_BAR; PG8_SCHED;
.LBB0_488:
	s_add_u32 s10, s34, 0xfffc0080
	s_addc_u32 s11, s35, -1
	s_add_i32 s77, 0, 0x10000
	s_cmp_eq_u32 s76, 4
	s_cselect_b32 s53, s45, s11
	s_cselect_b32 s52, s44, s10
	s_cselect_b32 s51, s49, s75
	s_cselect_b32 s50, s48, s19
	s_add_i32 s78, 0, 0x14000
	v_add_u32_e32 v140, s77, v246
	v_add_u32_e32 v156, s77, v246
	v_add_u32_e32 v156, 0x1000, v156
	ds_read_b128 v[128:131], v140
	ds_read_b128 v[132:135], v140 offset:1024
	ds_read_b128 v[136:139], v140 offset:2048
	ds_read_b128 v[140:143], v140 offset:3072
	ds_read_b128 v[144:147], v156
	ds_read_b128 v[148:151], v156 offset:1024
	ds_read_b128 v[152:155], v156 offset:2048
	ds_read_b128 v[156:159], v156 offset:3072
	v_lshl_add_u64 v[208:209], s[34:35], 0, v[204:205]
	s_add_i32 m0, s55, 0xc000
	ds_read_b128 v[160:163], v249
	ds_read_b128 v[164:167], v249 offset:1024
	ds_read_b128 v[168:171], v249 offset:2048
	ds_read_b128 v[172:175], v249 offset:3072
	ds_read_b128 v[176:179], v249 offset:4096
	ds_read_b128 v[180:183], v249 offset:5120
	ds_read_b128 v[184:187], v249 offset:6144
	ds_read_b128 v[188:191], v249 offset:7168
	global_load_lds_dwordx4 v[208:209], off
	v_lshl_add_u64 v[208:209], s[34:35], 0, v[206:207]
	s_add_i32 m0, s55, 0xe000
	s_nop 0
	global_load_lds_dwordx4 v[208:209], off
	s_setprio 1
	s_waitcnt vmcnt(8)
	s_waitcnt lgkmcnt(0)
	s_barrier
	v_mfma_f32_16x16x32_bf16 v[124:127], v[128:131], v[160:163], v[124:127]
	v_mfma_f32_16x16x32_bf16 v[120:123], v[136:139], v[160:163], v[120:123]
	v_mfma_f32_16x16x32_bf16 v[116:119], v[128:131], v[168:171], v[116:119]
	v_mfma_f32_16x16x32_bf16 v[112:115], v[136:139], v[168:171], v[112:115]
	v_mfma_f32_16x16x32_bf16 v[108:111], v[128:131], v[176:179], v[108:111]
	v_mfma_f32_16x16x32_bf16 v[104:107], v[136:139], v[176:179], v[104:107]
	v_mfma_f32_16x16x32_bf16 v[100:103], v[128:131], v[184:187], v[100:103]
	v_mfma_f32_16x16x32_bf16 v[96:99], v[136:139], v[184:187], v[96:99]
	v_mfma_f32_16x16x32_bf16 v[124:127], v[132:135], v[164:167], v[124:127]
	v_mfma_f32_16x16x32_bf16 v[120:123], v[140:143], v[164:167], v[120:123]
	v_mfma_f32_16x16x32_bf16 v[116:119], v[132:135], v[172:175], v[116:119]
	v_mfma_f32_16x16x32_bf16 v[112:115], v[140:143], v[172:175], v[112:115]
	v_mfma_f32_16x16x32_bf16 v[108:111], v[132:135], v[180:183], v[108:111]
	v_mfma_f32_16x16x32_bf16 v[104:107], v[140:143], v[180:183], v[104:107]
	v_mfma_f32_16x16x32_bf16 v[100:103], v[132:135], v[188:191], v[100:103]
	v_mfma_f32_16x16x32_bf16 v[96:99], v[140:143], v[188:191], v[96:99]
	s_setprio 0
	s_setprio 1
	v_mfma_f32_16x16x32_bf16 v[92:95], v[144:147], v[160:163], v[92:95]
	v_mfma_f32_16x16x32_bf16 v[88:91], v[152:155], v[160:163], v[88:91]
	v_mfma_f32_16x16x32_bf16 v[84:87], v[144:147], v[168:171], v[84:87]
	v_mfma_f32_16x16x32_bf16 v[80:83], v[152:155], v[168:171], v[80:83]
	v_mfma_f32_16x16x32_bf16 v[76:79], v[144:147], v[176:179], v[76:79]
	v_mfma_f32_16x16x32_bf16 v[72:75], v[152:155], v[176:179], v[72:75]
	v_mfma_f32_16x16x32_bf16 v[68:71], v[144:147], v[184:187], v[68:71]
	v_mfma_f32_16x16x32_bf16 v[64:67], v[152:155], v[184:187], v[64:67]
	v_mfma_f32_16x16x32_bf16 v[92:95], v[148:151], v[164:167], v[92:95]
	v_mfma_f32_16x16x32_bf16 v[88:91], v[156:159], v[164:167], v[88:91]
	v_mfma_f32_16x16x32_bf16 v[84:87], v[148:151], v[172:175], v[84:87]
	v_mfma_f32_16x16x32_bf16 v[80:83], v[156:159], v[172:175], v[80:83]
	v_mfma_f32_16x16x32_bf16 v[76:79], v[148:151], v[180:183], v[76:79]
	v_mfma_f32_16x16x32_bf16 v[72:75], v[156:159], v[180:183], v[72:75]
	v_mfma_f32_16x16x32_bf16 v[68:71], v[148:151], v[188:191], v[68:71]
	v_mfma_f32_16x16x32_bf16 v[64:67], v[156:159], v[188:191], v[64:67]
	s_barrier
	s_setprio 0
	s_add_i32 s10, s77, s14
	v_lshl_add_u64 v[208:209], s[50:51], 0, v[198:199]
	s_mov_b32 m0, s10
	ds_read_b128 v[160:163], v249 offset:16384
	ds_read_b128 v[164:167], v249 offset:17408
	ds_read_b128 v[168:171], v249 offset:18432
	ds_read_b128 v[172:175], v249 offset:19456
	ds_read_b128 v[176:179], v249 offset:20480
	ds_read_b128 v[180:183], v249 offset:21504
	ds_read_b128 v[184:187], v249 offset:22528
	ds_read_b128 v[188:191], v249 offset:23552
	global_load_lds_dwordx4 v[208:209], off
	s_add_i32 m0, s10, 0x2000
	s_add_u32 s10, s50, 0x40000
	v_lshl_add_u64 v[210:211], s[50:51], 0, v[194:195]
	s_addc_u32 s11, s51, 0
	s_add_i32 s77, s78, s14
	global_load_lds_dwordx4 v[210:211], off
	v_lshl_add_u64 v[212:213], s[10:11], 0, v[198:199]
	s_mov_b32 m0, s77
	v_lshl_add_u64 v[214:215], s[52:53], 0, v[196:197]
	global_load_lds_dwordx4 v[212:213], off
	v_lshl_add_u64 v[212:213], s[10:11], 0, v[194:195]
	s_add_i32 m0, s77, 0x2000
	s_nop 0
	global_load_lds_dwordx4 v[212:213], off
	v_lshl_add_u64 v[212:213], s[52:53], 0, v[200:201]
	s_mov_b32 m0, s55
	s_nop 0
	global_load_lds_dwordx4 v[212:213], off
	s_mov_b32 m0, s58
	s_nop 0
	global_load_lds_dwordx4 v[214:215], off
	s_setprio 1
	s_waitcnt vmcnt(8)
	s_waitcnt lgkmcnt(0)
	s_barrier
; #define PG8_STAGE(bufoff, gbase, voff) do { _Pragma("unroll") for (int _i = 0; _i < 2; ++_i) \
;         __builtin_amdgcn_global_load_lds((const unsigned*)((const char*)(gbase) + (voff)[_i]), (PG8_LAS unsigned*)(lds + (bufoff) + ldsw + _i * 8192), 16, 0, 0); } while (0)
; #define PG8_LDA(dst, b, h) do { _Pragma("unroll") for (int m = 0; m < 4; ++m) _Pragma("unroll") for (int k = 0; k < 2; ++k) dst[m][k] = *(const PG8_LAS bf16x8*)(lds + PG8_SA(b, h) + aoff + m * 2048 + k * 1024); } while (0)
; #define PG8_LDB(dst, b, h) do { _Pragma("unroll") for (int n = 0; n < 2; ++n) _Pragma("unroll") for (int k = 0; k < 2; ++k) dst[n][k] = *(const PG8_LAS bf16x8*)(lds + PG8_SB(b, h) + boff + n * 2048 + k * 1024); } while (0)
; #define PG8_MMA(ai, bj, At, Bt) do { __builtin_amdgcn_s_setprio(1); _Pragma("unroll") for (int m = 0; m < 4; ++m) _Pragma("unroll") for (int n = 0; n < 2; ++n) _Pragma("unroll") for (int k = 0; k < 2; ++k) \
;         acc[ai][bj][m][n] = __builtin_amdgcn_mfma_f32_16x16x32_bf16(Bt[n][k], At[m][k], acc[ai][bj][m][n], 0, 0, 0); __builtin_amdgcn_s_setprio(0); } while (0)
; #define PG8_WAIT_V(n) asm volatile("s_waitcnt vmcnt(" #n ")" ::: "memory")
; #define PG8_WAIT_L(n) asm volatile("s_waitcnt lgkmcnt(" #n ")" ::: "memory")
; #define PG8_BAR __builtin_amdgcn_s_barrier()
; #define PG8_SCHED __builtin_amdgcn_sched_barrier(0)
; template <class Epi, class Sched, bool ALIGN_EPI = false, bool SP2 = false>
; __device__ __forceinline__ void gemm_phase(PG8_LAS unsigned char* lds, const Gemm g, const Sched& S, const Epi& E) {
;     ...
;             PG8_WAIT_V(8); PG8_WAIT_L(0); PG8_BAR; PG8_MMA(1, 0, At, B0); PG8_MMA(1, 1, At, B1); PG8_BAR; PG8_SCHED;
;             PG8_LDB(B0, 1, 0); PG8_LDB(B1, 1, 1); PG8_SCHED; PG8_LDA(At, 1, 0); PG8_STAGE(PG8_SA(0, 1), a2 + hstep, voffA);
;             PG8_WAIT_V(8); PG8_WAIT_L(0); PG8_BAR; PG8_MMA(0, 0, At, B0); PG8_MMA(0, 1, At, B1); PG8_BAR; PG8_SCHED;
	v_mfma_f32_16x16x32_bf16 v[60:63], v[128:131], v[160:163], v[60:63]
	v_mfma_f32_16x16x32_bf16 v[56:59], v[136:139], v[160:163], v[56:59]
	v_mfma_f32_16x16x32_bf16 v[52:55], v[128:131], v[168:171], v[52:55]
	v_mfma_f32_16x16x32_bf16 v[48:51], v[136:139], v[168:171], v[48:51]
	v_mfma_f32_16x16x32_bf16 v[44:47], v[128:131], v[176:179], v[44:47]
	v_mfma_f32_16x16x32_bf16 v[40:43], v[136:139], v[176:179], v[40:43]
	v_mfma_f32_16x16x32_bf16 v[36:39], v[128:131], v[184:187], v[36:39]
	v_mfma_f32_16x16x32_bf16 v[32:35], v[136:139], v[184:187], v[32:35]
	v_mfma_f32_16x16x32_bf16 v[60:63], v[132:135], v[164:167], v[60:63]
	v_mfma_f32_16x16x32_bf16 v[56:59], v[140:143], v[164:167], v[56:59]
	v_mfma_f32_16x16x32_bf16 v[52:55], v[132:135], v[172:175], v[52:55]
	v_mfma_f32_16x16x32_bf16 v[48:51], v[140:143], v[172:175], v[48:51]
	v_mfma_f32_16x16x32_bf16 v[44:47], v[132:135], v[180:183], v[44:47]
	v_mfma_f32_16x16x32_bf16 v[40:43], v[140:143], v[180:183], v[40:43]
	v_mfma_f32_16x16x32_bf16 v[36:39], v[132:135], v[188:191], v[36:39]
	v_mfma_f32_16x16x32_bf16 v[32:35], v[140:143], v[188:191], v[32:35]
	s_setprio 0
	s_setprio 1
	v_mfma_f32_16x16x32_bf16 v[28:31], v[144:147], v[160:163], v[28:31]
	v_mfma_f32_16x16x32_bf16 v[24:27], v[152:155], v[160:163], v[24:27]
	v_mfma_f32_16x16x32_bf16 v[20:23], v[144:147], v[168:171], v[20:23]
	v_mfma_f32_16x16x32_bf16 v[16:19], v[152:155], v[168:171], v[16:19]
	v_mfma_f32_16x16x32_bf16 v[12:15], v[144:147], v[176:179], v[12:15]
	v_mfma_f32_16x16x32_bf16 v[8:11], v[152:155], v[176:179], v[8:11]
	v_mfma_f32_16x16x32_bf16 v[4:7], v[144:147], v[184:187], v[4:7]
	v_mfma_f32_16x16x32_bf16 v[0:3], v[152:155], v[184:187], v[0:3]
	v_mfma_f32_16x16x32_bf16 v[28:31], v[148:151], v[164:167], v[28:31]
	v_mfma_f32_16x16x32_bf16 v[24:27], v[156:159], v[164:167], v[24:27]
	v_mfma_f32_16x16x32_bf16 v[20:23], v[148:151], v[172:175], v[20:23]
	v_mfma_f32_16x16x32_bf16 v[16:19], v[156:159], v[172:175], v[16:19]
	v_mfma_f32_16x16x32_bf16 v[12:15], v[148:151], v[180:183], v[12:15]
	v_mfma_f32_16x16x32_bf16 v[8:11], v[156:159], v[180:183], v[8:11]
	v_mfma_f32_16x16x32_bf16 v[4:7], v[148:151], v[188:191], v[4:7]
	v_mfma_f32_16x16x32_bf16 v[0:3], v[156:159], v[188:191], v[0:3]
	s_barrier
	s_setprio 0
	s_add_i32 s77, 0, 0x18000
	s_add_i32 s78, 0, 0x1c000
	v_add_u32_e32 v140, s77, v246
	v_add_u32_e32 v156, s77, v246
	v_add_u32_e32 v156, 0x1000, v156
	ds_read_b128 v[128:131], v140
	ds_read_b128 v[132:135], v140 offset:1024
	ds_read_b128 v[136:139], v140 offset:2048
	ds_read_b128 v[140:143], v140 offset:3072
	ds_read_b128 v[144:147], v156
	ds_read_b128 v[148:151], v156 offset:1024
	ds_read_b128 v[152:155], v156 offset:2048
	ds_read_b128 v[156:159], v156 offset:3072
	s_add_u32 s10, s52, 0x40000
	s_addc_u32 s11, s53, 0
	s_mov_b32 m0, s59
	v_lshl_add_u64 v[216:217], s[10:11], 0, v[200:201]
	ds_read_b128 v[160:163], v249 offset:32768
	ds_read_b128 v[164:167], v249 offset:33792
	ds_read_b128 v[168:171], v249 offset:34816
	ds_read_b128 v[172:175], v249 offset:35840
	ds_read_b128 v[176:179], v249 offset:36864
	ds_read_b128 v[180:183], v249 offset:37888
	ds_read_b128 v[184:187], v249 offset:38912
	ds_read_b128 v[188:191], v249 offset:39936
	global_load_lds_dwordx4 v[216:217], off
	v_lshl_add_u64 v[216:217], s[10:11], 0, v[196:197]
	s_mov_b32 m0, s60
	s_nop 0
	global_load_lds_dwordx4 v[216:217], off
	s_setprio 1
	s_waitcnt vmcnt(8)
	s_waitcnt lgkmcnt(0)
	s_barrier
	v_mfma_f32_16x16x32_bf16 v[124:127], v[128:131], v[160:163], v[124:127]
	v_mfma_f32_16x16x32_bf16 v[120:123], v[136:139], v[160:163], v[120:123]
	v_mfma_f32_16x16x32_bf16 v[116:119], v[128:131], v[168:171], v[116:119]
	v_mfma_f32_16x16x32_bf16 v[112:115], v[136:139], v[168:171], v[112:115]
	v_mfma_f32_16x16x32_bf16 v[108:111], v[128:131], v[176:179], v[108:111]
	v_mfma_f32_16x16x32_bf16 v[104:107], v[136:139], v[176:179], v[104:107]
	v_mfma_f32_16x16x32_bf16 v[100:103], v[128:131], v[184:187], v[100:103]
	v_mfma_f32_16x16x32_bf16 v[96:99], v[136:139], v[184:187], v[96:99]
	v_mfma_f32_16x16x32_bf16 v[124:127], v[132:135], v[164:167], v[124:127]
	v_mfma_f32_16x16x32_bf16 v[120:123], v[140:143], v[164:167], v[120:123]
	v_mfma_f32_16x16x32_bf16 v[116:119], v[132:135], v[172:175], v[116:119]
	v_mfma_f32_16x16x32_bf16 v[112:115], v[140:143], v[172:175], v[112:115]
	v_mfma_f32_16x16x32_bf16 v[108:111], v[132:135], v[180:183], v[108:111]
	v_mfma_f32_16x16x32_bf16 v[104:107], v[140:143], v[180:183], v[104:107]
	v_mfma_f32_16x16x32_bf16 v[100:103], v[132:135], v[188:191], v[100:103]
	v_mfma_f32_16x16x32_bf16 v[96:99], v[140:143], v[188:191], v[96:99]
	s_setprio 0
	s_setprio 1
	v_mfma_f32_16x16x32_bf16 v[92:95], v[144:147], v[160:163], v[92:95]
	v_mfma_f32_16x16x32_bf16 v[88:91], v[152:155], v[160:163], v[88:91]
	v_mfma_f32_16x16x32_bf16 v[84:87], v[144:147], v[168:171], v[84:87]
	v_mfma_f32_16x16x32_bf16 v[80:83], v[152:155], v[168:171], v[80:83]
	v_mfma_f32_16x16x32_bf16 v[76:79], v[144:147], v[176:179], v[76:79]
	v_mfma_f32_16x16x32_bf16 v[72:75], v[152:155], v[176:179], v[72:75]
	v_mfma_f32_16x16x32_bf16 v[68:71], v[144:147], v[184:187], v[68:71]
	v_mfma_f32_16x16x32_bf16 v[64:67], v[152:155], v[184:187], v[64:67]
	v_mfma_f32_16x16x32_bf16 v[92:95], v[148:151], v[164:167], v[92:95]
	v_mfma_f32_16x16x32_bf16 v[88:91], v[156:159], v[164:167], v[88:91]
	v_mfma_f32_16x16x32_bf16 v[84:87], v[148:151], v[172:175], v[84:87]
	v_mfma_f32_16x16x32_bf16 v[80:83], v[156:159], v[172:175], v[80:83]
	v_mfma_f32_16x16x32_bf16 v[76:79], v[148:151], v[180:183], v[76:79]
	v_mfma_f32_16x16x32_bf16 v[72:75], v[156:159], v[180:183], v[72:75]
	v_mfma_f32_16x16x32_bf16 v[68:71], v[148:151], v[188:191], v[68:71]
	v_mfma_f32_16x16x32_bf16 v[64:67], v[156:159], v[188:191], v[64:67]
	s_barrier
; #define PG8_STAGE(bufoff, gbase, voff) do { _Pragma("unroll") for (int _i = 0; _i < 2; ++_i) \
;         __builtin_amdgcn_global_load_lds((const unsigned*)((const char*)(gbase) + (voff)[_i]), (PG8_LAS unsigned*)(lds + (bufoff) + ldsw + _i * 8192), 16, 0, 0); } while (0)
; #define PG8_LDA(dst, b, h) do { _Pragma("unroll") for (int m = 0; m < 4; ++m) _Pragma("unroll") for (int k = 0; k < 2; ++k) dst[m][k] = *(const PG8_LAS bf16x8*)(lds + PG8_SA(b, h) + aoff + m * 2048 + k * 1024); } while (0)
; #define PG8_MMA(ai, bj, At, Bt) do { __builtin_amdgcn_s_setprio(1); _Pragma("unroll") for (int m = 0; m < 4; ++m) _Pragma("unroll") for (int n = 0; n < 2; ++n) _Pragma("unroll") for (int k = 0; k < 2; ++k) \
;         acc[ai][bj][m][n] = __builtin_amdgcn_mfma_f32_16x16x32_bf16(Bt[n][k], At[m][k], acc[ai][bj][m][n], 0, 0, 0); __builtin_amdgcn_s_setprio(0); } while (0)
; #define PG8_WAIT_V(n) asm volatile("s_waitcnt vmcnt(" #n ")" ::: "memory")
; #define PG8_WAIT_L(n) asm volatile("s_waitcnt lgkmcnt(" #n ")" ::: "memory")
; #define PG8_BAR __builtin_amdgcn_s_barrier()
; #define PG8_SCHED __builtin_amdgcn_sched_barrier(0)
; template <class Epi, class Sched, bool ALIGN_EPI = false, bool SP2 = false>
; __device__ __forceinline__ void gemm_phase(PG8_LAS unsigned char* lds, const Gemm g, const Sched& S, const Epi& E) {
;     ...
;             PG8_LDA(At, 1, 1); PG8_STAGE(PG8_SB(1, 0), b3, voffB); PG8_STAGE(PG8_SB(1, 1), b3 + hstep, voffB); PG8_STAGE(PG8_SA(1, 0), a3, voffA);
;             PG8_WAIT_V(8); PG8_WAIT_L(0); PG8_BAR; PG8_MMA(1, 0, At, B0); PG8_MMA(1, 1, At, B1); PG8_BAR; PG8_SCHED;
;     ...
;         if constexpr (ALIGN_EPI) { if (wr == 0) PG8_BAR; }
	s_setprio 0
	s_add_i32 s10, s77, s14
	v_lshl_add_u64 v[208:209], v[208:209], 0, s[36:37]
	s_mov_b32 m0, s10
	ds_read_b128 v[160:163], v249 offset:49152
	ds_read_b128 v[164:167], v249 offset:50176
	ds_read_b128 v[168:171], v249 offset:51200
	ds_read_b128 v[172:175], v249 offset:52224
	ds_read_b128 v[176:179], v249 offset:53248
	ds_read_b128 v[180:183], v249 offset:54272
	ds_read_b128 v[184:187], v249 offset:55296
	ds_read_b128 v[188:191], v249 offset:56320
	global_load_lds_dwordx4 v[208:209], off
	s_add_i32 m0, s10, 0x2000
	s_add_u32 s10, s50, 0x40080
	v_lshl_add_u64 v[208:209], v[210:211], 0, s[36:37]
	s_addc_u32 s11, s51, 0
	s_add_i32 s50, s78, s14
	global_load_lds_dwordx4 v[208:209], off
	v_lshl_add_u64 v[208:209], s[10:11], 0, v[198:199]
	s_mov_b32 m0, s50
	s_nop 0
	global_load_lds_dwordx4 v[208:209], off
	v_lshl_add_u64 v[208:209], s[10:11], 0, v[194:195]
	s_add_i32 m0, s50, 0x2000
	s_nop 0
	global_load_lds_dwordx4 v[208:209], off
	v_lshl_add_u64 v[208:209], v[212:213], 0, s[36:37]
	s_mov_b32 m0, s65
	s_nop 0
	global_load_lds_dwordx4 v[208:209], off
	v_lshl_add_u64 v[208:209], v[214:215], 0, s[36:37]
	s_mov_b32 m0, s66
	s_nop 0
	global_load_lds_dwordx4 v[208:209], off
	s_setprio 1
	s_waitcnt vmcnt(8)
	s_waitcnt lgkmcnt(0)
	s_barrier
	v_mfma_f32_16x16x32_bf16 v[60:63], v[128:131], v[160:163], v[60:63]
	v_mfma_f32_16x16x32_bf16 v[56:59], v[136:139], v[160:163], v[56:59]
	v_mfma_f32_16x16x32_bf16 v[52:55], v[128:131], v[168:171], v[52:55]
	v_mfma_f32_16x16x32_bf16 v[48:51], v[136:139], v[168:171], v[48:51]
	v_mfma_f32_16x16x32_bf16 v[44:47], v[128:131], v[176:179], v[44:47]
	v_mfma_f32_16x16x32_bf16 v[40:43], v[136:139], v[176:179], v[40:43]
	v_mfma_f32_16x16x32_bf16 v[36:39], v[128:131], v[184:187], v[36:39]
	v_mfma_f32_16x16x32_bf16 v[32:35], v[136:139], v[184:187], v[32:35]
	v_mfma_f32_16x16x32_bf16 v[60:63], v[132:135], v[164:167], v[60:63]
	v_mfma_f32_16x16x32_bf16 v[56:59], v[140:143], v[164:167], v[56:59]
	v_mfma_f32_16x16x32_bf16 v[52:55], v[132:135], v[172:175], v[52:55]
	v_mfma_f32_16x16x32_bf16 v[48:51], v[140:143], v[172:175], v[48:51]
	v_mfma_f32_16x16x32_bf16 v[44:47], v[132:135], v[180:183], v[44:47]
	v_mfma_f32_16x16x32_bf16 v[40:43], v[140:143], v[180:183], v[40:43]
	v_mfma_f32_16x16x32_bf16 v[36:39], v[132:135], v[188:191], v[36:39]
	v_mfma_f32_16x16x32_bf16 v[32:35], v[140:143], v[188:191], v[32:35]
	s_setprio 0
	s_setprio 1
	v_mfma_f32_16x16x32_bf16 v[28:31], v[144:147], v[160:163], v[28:31]
	v_mfma_f32_16x16x32_bf16 v[24:27], v[152:155], v[160:163], v[24:27]
	v_mfma_f32_16x16x32_bf16 v[20:23], v[144:147], v[168:171], v[20:23]
	v_mfma_f32_16x16x32_bf16 v[16:19], v[152:155], v[168:171], v[16:19]
	v_mfma_f32_16x16x32_bf16 v[12:15], v[144:147], v[176:179], v[12:15]
	v_mfma_f32_16x16x32_bf16 v[8:11], v[152:155], v[176:179], v[8:11]
	v_mfma_f32_16x16x32_bf16 v[4:7], v[144:147], v[184:187], v[4:7]
	v_mfma_f32_16x16x32_bf16 v[0:3], v[152:155], v[184:187], v[0:3]
	v_mfma_f32_16x16x32_bf16 v[28:31], v[148:151], v[164:167], v[28:31]
	v_mfma_f32_16x16x32_bf16 v[24:27], v[156:159], v[164:167], v[24:27]
	v_mfma_f32_16x16x32_bf16 v[20:23], v[148:151], v[172:175], v[20:23]
	v_mfma_f32_16x16x32_bf16 v[16:19], v[156:159], v[172:175], v[16:19]
	v_mfma_f32_16x16x32_bf16 v[12:15], v[148:151], v[180:183], v[12:15]
	v_mfma_f32_16x16x32_bf16 v[8:11], v[156:159], v[180:183], v[8:11]
	v_mfma_f32_16x16x32_bf16 v[4:7], v[148:151], v[188:191], v[4:7]
	v_mfma_f32_16x16x32_bf16 v[0:3], v[156:159], v[188:191], v[0:3]
	s_barrier
	s_setprio 0
	s_add_i32 s76, s76, 2
	s_add_u32 s34, s34, 0x100
	s_addc_u32 s35, s35, 0
	s_add_u32 s19, s19, 0x100
	s_addc_u32 s75, s75, 0
	s_cmp_gt_u32 s76, 5
	s_cbranch_scc0 .LBB0_488
	s_and_b64 vcc, exec, s[24:25]
	s_cbranch_vccz .LBB0_491
	s_barrier

; #define PG8_STAGE(bufoff, gbase, voff) do { _Pragma("unroll") for (int _i = 0; _i < 2; ++_i) \
;         __builtin_amdgcn_global_load_lds((const unsigned*)((const char*)(gbase) + (voff)[_i]), (PG8_LAS unsigned*)(lds + (bufoff) + ldsw + _i * 8192), 16, 0, 0); } while (0)
; #define PG8_LDA(dst, b, h) do { _Pragma("unroll") for (int m = 0; m < 4; ++m) _Pragma("unroll") for (int k = 0; k < 2; ++k) dst[m][k] = *(const PG8_LAS bf16x8*)(lds + PG8_SA(b, h) + aoff + m * 2048 + k * 1024); } while (0)
; #define PG8_LDB(dst, b, h) do { _Pragma("unroll") for (int n = 0; n < 2; ++n) _Pragma("unroll") for (int k = 0; k < 2; ++k) dst[n][k] = *(const PG8_LAS bf16x8*)(lds + PG8_SB(b, h) + boff + n * 2048 + k * 1024); } while (0)
; #define PG8_MMA(ai, bj, At, Bt) do { __builtin_amdgcn_s_setprio(1); _Pragma("unroll") for (int m = 0; m < 4; ++m) _Pragma("unroll") for (int n = 0; n < 2; ++n) _Pragma("unroll") for (int k = 0; k < 2; ++k) \
;         acc[ai][bj][m][n] = __builtin_amdgcn_mfma_f32_16x16x32_bf16(Bt[n][k], At[m][k], acc[ai][bj][m][n], 0, 0, 0); __builtin_amdgcn_s_setprio(0); } while (0)
; #define PG8_WAIT_V(n) asm volatile("s_waitcnt vmcnt(" #n ")" ::: "memory")
; #define PG8_WAIT_L(n) asm volatile("s_waitcnt lgkmcnt(" #n ")" ::: "memory")
; template <class Epi, class Sched, bool ALIGN_EPI = false, bool SP2 = false>
; __device__ __forceinline__ void gemm_phase(PG8_LAS unsigned char* lds, const Gemm g, const Sched& S, const Epi& E) {
;     ...
;             const bool last = (t == nt - 2);
;             const char* a1 = cA + (size_t)(t + 1) * kstep;
;             const char* a2 = last ? nA : cA + (size_t)(t + 2) * kstep; const char* b2 = last ? nB : cB + (size_t)(t + 2) * kstep;
;             const char* a3 = a2 + kstep; const char* b3 = b2 + kstep;
;             if (last && has_next) S.a_ready(nxt);
;             if constexpr (SP2) {
;             PG8_LDB(B0, 0, 0); PG8_LDB(B1, 0, 1); PG8_SCHED; PG8_LDA(At, 0, 0); PG8_STAGE(PG8_SA(1, 1), a1 + hstep, voffA);
;             PG8_WAIT_V(8); PG8_WAIT_L(0); PG8_BAR; PG8_MMA(0, 0, At, B0); PG8_MMA(0, 1, At, B1); PG8_BAR; PG8_SCHED;
;             PG8_LDA(At, 0, 1); PG8_STAGE(PG8_SB(0, 0), b2, voffB); PG8_STAGE(PG8_SB(0, 1), b2 + hstep, voffB); PG8_STAGE(PG8_SA(0, 0), a2, voffA);
;             PG8_WAIT_V(8); PG8_WAIT_L(0); PG8_BAR; PG8_MMA(1, 0, At, B0); PG8_MMA(1, 1, At, B1); PG8_BAR; PG8_SCHED;
.LBB0_577:
	s_add_u32 s10, s44, 0xfffc0080
	s_addc_u32 s11, s45, -1
	s_add_i32 s64, 0, 0x10000
	s_cmp_eq_u32 s63, 12
	s_cselect_b32 s49, s29, s11
	s_cselect_b32 s48, s43, s10
	v_add_u32_e32 v146, s64, v149
	s_cselect_b32 s47, s27, s62
	s_cselect_b32 s46, s60, s61
	s_add_i32 s65, 0, 0x14000
	ds_read_b128 v[128:131], v146
	ds_read_b128 v[154:157], v146 offset:1024
	ds_read_b128 v[158:161], v146 offset:2048
	ds_read_b128 v[162:165], v146 offset:3072
	v_add_u32_e32 v146, s65, v149
	ds_read_b128 v[166:169], v146
	ds_read_b128 v[170:173], v146 offset:1024
	ds_read_b128 v[174:177], v146 offset:2048
	ds_read_b128 v[178:181], v146 offset:3072
	v_lshl_add_u64 v[190:191], s[44:45], 0, v[142:143]
	s_add_i32 m0, s51, 0xc000
	ds_read_b128 v[182:185], v153
	ds_read_b128 v[186:189], v153 offset:1024
	ds_read_b128 v[194:197], v153 offset:2048
	ds_read_b128 v[198:201], v153 offset:3072
	ds_read_b128 v[202:205], v153 offset:4096
	ds_read_b128 v[206:209], v153 offset:5120
	ds_read_b128 v[210:213], v153 offset:6144
	ds_read_b128 v[214:217], v153 offset:7168
	global_load_lds_dwordx4 v[190:191], off
	v_lshl_add_u64 v[190:191], s[44:45], 0, v[144:145]
	s_add_i32 m0, s51, 0xe000
	s_nop 0
	global_load_lds_dwordx4 v[190:191], off
	s_setprio 1
	s_waitcnt vmcnt(8)
	s_waitcnt lgkmcnt(0)
	s_barrier
	v_mfma_f32_16x16x32_bf16 v[124:127], v[128:131], v[182:185], v[124:127]
	v_mfma_f32_16x16x32_bf16 v[116:119], v[158:161], v[182:185], v[116:119]
	v_mfma_f32_16x16x32_bf16 v[108:111], v[128:131], v[194:197], v[108:111]
	v_mfma_f32_16x16x32_bf16 v[100:103], v[158:161], v[194:197], v[100:103]
	v_mfma_f32_16x16x32_bf16 v[92:95], v[128:131], v[202:205], v[92:95]
	v_mfma_f32_16x16x32_bf16 v[84:87], v[158:161], v[202:205], v[84:87]
	v_mfma_f32_16x16x32_bf16 v[76:79], v[128:131], v[210:213], v[76:79]
	v_mfma_f32_16x16x32_bf16 v[68:71], v[158:161], v[210:213], v[68:71]
	v_mfma_f32_16x16x32_bf16 v[124:127], v[154:157], v[186:189], v[124:127]
	v_mfma_f32_16x16x32_bf16 v[116:119], v[162:165], v[186:189], v[116:119]
	v_mfma_f32_16x16x32_bf16 v[108:111], v[154:157], v[198:201], v[108:111]
	v_mfma_f32_16x16x32_bf16 v[100:103], v[162:165], v[198:201], v[100:103]
	v_mfma_f32_16x16x32_bf16 v[92:95], v[154:157], v[206:209], v[92:95]
	v_mfma_f32_16x16x32_bf16 v[84:87], v[162:165], v[206:209], v[84:87]
	v_mfma_f32_16x16x32_bf16 v[76:79], v[154:157], v[214:217], v[76:79]
	v_mfma_f32_16x16x32_bf16 v[68:71], v[162:165], v[214:217], v[68:71]
	s_setprio 0
	s_setprio 1
	v_mfma_f32_16x16x32_bf16 v[120:123], v[166:169], v[182:185], v[120:123]
	v_mfma_f32_16x16x32_bf16 v[112:115], v[174:177], v[182:185], v[112:115]
	v_mfma_f32_16x16x32_bf16 v[104:107], v[166:169], v[194:197], v[104:107]
	v_mfma_f32_16x16x32_bf16 v[96:99], v[174:177], v[194:197], v[96:99]
	v_mfma_f32_16x16x32_bf16 v[88:91], v[166:169], v[202:205], v[88:91]
	v_mfma_f32_16x16x32_bf16 v[80:83], v[174:177], v[202:205], v[80:83]
	v_mfma_f32_16x16x32_bf16 v[72:75], v[166:169], v[210:213], v[72:75]
	v_mfma_f32_16x16x32_bf16 v[64:67], v[174:177], v[210:213], v[64:67]
	v_mfma_f32_16x16x32_bf16 v[120:123], v[170:173], v[186:189], v[120:123]
	v_mfma_f32_16x16x32_bf16 v[112:115], v[178:181], v[186:189], v[112:115]
	v_mfma_f32_16x16x32_bf16 v[104:107], v[170:173], v[198:201], v[104:107]
	v_mfma_f32_16x16x32_bf16 v[96:99], v[178:181], v[198:201], v[96:99]
	v_mfma_f32_16x16x32_bf16 v[88:91], v[170:173], v[206:209], v[88:91]
	v_mfma_f32_16x16x32_bf16 v[80:83], v[178:181], v[206:209], v[80:83]
	v_mfma_f32_16x16x32_bf16 v[72:75], v[170:173], v[214:217], v[72:75]
	v_mfma_f32_16x16x32_bf16 v[64:67], v[178:181], v[214:217], v[64:67]
	s_barrier
	s_setprio 0
	s_add_i32 s10, s64, s19
	v_lshl_add_u64 v[190:191], s[46:47], 0, v[136:137]
	s_mov_b32 m0, s10
	ds_read_b128 v[182:185], v153 offset:16384
	ds_read_b128 v[186:189], v153 offset:17408
	ds_read_b128 v[194:197], v153 offset:18432
	ds_read_b128 v[198:201], v153 offset:19456
	ds_read_b128 v[202:205], v153 offset:20480
	ds_read_b128 v[206:209], v153 offset:21504
	ds_read_b128 v[210:213], v153 offset:22528
	ds_read_b128 v[214:217], v153 offset:23552
	global_load_lds_dwordx4 v[190:191], off
	s_add_i32 m0, s10, 0x2000
	s_add_u32 s10, s46, 0x40000
	v_lshl_add_u64 v[218:219], s[46:47], 0, v[132:133]
	s_addc_u32 s11, s47, 0
	s_add_i32 s64, s65, s19
	global_load_lds_dwordx4 v[218:219], off
	v_lshl_add_u64 v[220:221], s[10:11], 0, v[136:137]
	s_mov_b32 m0, s64
	v_lshl_add_u64 v[222:223], s[48:49], 0, v[134:135]
	global_load_lds_dwordx4 v[220:221], off
	v_lshl_add_u64 v[220:221], s[10:11], 0, v[132:133]
	s_add_i32 m0, s64, 0x2000
	s_nop 0
	global_load_lds_dwordx4 v[220:221], off
	v_lshl_add_u64 v[220:221], s[48:49], 0, v[138:139]
	s_mov_b32 m0, s51
	s_nop 0
	global_load_lds_dwordx4 v[220:221], off
	s_mov_b32 m0, s52
	s_nop 0
	global_load_lds_dwordx4 v[222:223], off
	s_setprio 1
	s_waitcnt vmcnt(8)
	s_waitcnt lgkmcnt(0)
	s_barrier
; #define PG8_STAGE(bufoff, gbase, voff) do { _Pragma("unroll") for (int _i = 0; _i < 2; ++_i) \
;         __builtin_amdgcn_global_load_lds((const unsigned*)((const char*)(gbase) + (voff)[_i]), (PG8_LAS unsigned*)(lds + (bufoff) + ldsw + _i * 8192), 16, 0, 0); } while (0)
; #define PG8_LDA(dst, b, h) do { _Pragma("unroll") for (int m = 0; m < 4; ++m) _Pragma("unroll") for (int k = 0; k < 2; ++k) dst[m][k] = *(const PG8_LAS bf16x8*)(lds + PG8_SA(b, h) + aoff + m * 2048 + k * 1024); } while (0)
; #define PG8_LDB(dst, b, h) do { _Pragma("unroll") for (int n = 0; n < 2; ++n) _Pragma("unroll") for (int k = 0; k < 2; ++k) dst[n][k] = *(const PG8_LAS bf16x8*)(lds + PG8_SB(b, h) + boff + n * 2048 + k * 1024); } while (0)
; #define PG8_MMA(ai, bj, At, Bt) do { __builtin_amdgcn_s_setprio(1); _Pragma("unroll") for (int m = 0; m < 4; ++m) _Pragma("unroll") for (int n = 0; n < 2; ++n) _Pragma("unroll") for (int k = 0; k < 2; ++k) \
;         acc[ai][bj][m][n] = __builtin_amdgcn_mfma_f32_16x16x32_bf16(Bt[n][k], At[m][k], acc[ai][bj][m][n], 0, 0, 0); __builtin_amdgcn_s_setprio(0); } while (0)
; #define PG8_WAIT_V(n) asm volatile("s_waitcnt vmcnt(" #n ")" ::: "memory")
; #define PG8_WAIT_L(n) asm volatile("s_waitcnt lgkmcnt(" #n ")" ::: "memory")
; #define PG8_BAR __builtin_amdgcn_s_barrier()
; #define PG8_SCHED __builtin_amdgcn_sched_barrier(0)
; template <class Epi, class Sched, bool ALIGN_EPI = false, bool SP2 = false>
; __device__ __forceinline__ void gemm_phase(PG8_LAS unsigned char* lds, const Gemm g, const Sched& S, const Epi& E) {
;     ...
;             PG8_WAIT_V(8); PG8_WAIT_L(0); PG8_BAR; PG8_MMA(1, 0, At, B0); PG8_MMA(1, 1, At, B1); PG8_BAR; PG8_SCHED;
;             PG8_LDB(B0, 1, 0); PG8_LDB(B1, 1, 1); PG8_SCHED; PG8_LDA(At, 1, 0); PG8_STAGE(PG8_SA(0, 1), a2 + hstep, voffA);
;             PG8_WAIT_V(8); PG8_WAIT_L(0); PG8_BAR; PG8_MMA(0, 0, At, B0); PG8_MMA(0, 1, At, B1); PG8_BAR; PG8_SCHED;
	v_mfma_f32_16x16x32_bf16 v[60:63], v[128:131], v[182:185], v[60:63]
	v_mfma_f32_16x16x32_bf16 v[52:55], v[158:161], v[182:185], v[52:55]
	v_mfma_f32_16x16x32_bf16 v[44:47], v[128:131], v[194:197], v[44:47]
	v_mfma_f32_16x16x32_bf16 v[36:39], v[158:161], v[194:197], v[36:39]
	v_mfma_f32_16x16x32_bf16 v[28:31], v[128:131], v[202:205], v[28:31]
	v_mfma_f32_16x16x32_bf16 v[20:23], v[158:161], v[202:205], v[20:23]
	v_mfma_f32_16x16x32_bf16 v[12:15], v[128:131], v[210:213], v[12:15]
	v_mfma_f32_16x16x32_bf16 v[4:7], v[158:161], v[210:213], v[4:7]
	v_mfma_f32_16x16x32_bf16 v[60:63], v[154:157], v[186:189], v[60:63]
	v_mfma_f32_16x16x32_bf16 v[52:55], v[162:165], v[186:189], v[52:55]
	v_mfma_f32_16x16x32_bf16 v[44:47], v[154:157], v[198:201], v[44:47]
	v_mfma_f32_16x16x32_bf16 v[36:39], v[162:165], v[198:201], v[36:39]
	v_mfma_f32_16x16x32_bf16 v[28:31], v[154:157], v[206:209], v[28:31]
	v_mfma_f32_16x16x32_bf16 v[20:23], v[162:165], v[206:209], v[20:23]
	v_mfma_f32_16x16x32_bf16 v[12:15], v[154:157], v[214:217], v[12:15]
	v_mfma_f32_16x16x32_bf16 v[4:7], v[162:165], v[214:217], v[4:7]
	s_setprio 0
	s_setprio 1
	v_mfma_f32_16x16x32_bf16 v[56:59], v[166:169], v[182:185], v[56:59]
	v_mfma_f32_16x16x32_bf16 v[48:51], v[174:177], v[182:185], v[48:51]
	v_mfma_f32_16x16x32_bf16 v[40:43], v[166:169], v[194:197], v[40:43]
	v_mfma_f32_16x16x32_bf16 v[32:35], v[174:177], v[194:197], v[32:35]
	v_mfma_f32_16x16x32_bf16 v[24:27], v[166:169], v[202:205], v[24:27]
	v_mfma_f32_16x16x32_bf16 v[16:19], v[174:177], v[202:205], v[16:19]
	v_mfma_f32_16x16x32_bf16 v[8:11], v[166:169], v[210:213], v[8:11]
	v_mfma_f32_16x16x32_bf16 v[0:3], v[174:177], v[210:213], v[0:3]
	v_mfma_f32_16x16x32_bf16 v[56:59], v[170:173], v[186:189], v[56:59]
	v_mfma_f32_16x16x32_bf16 v[48:51], v[178:181], v[186:189], v[48:51]
	v_mfma_f32_16x16x32_bf16 v[40:43], v[170:173], v[198:201], v[40:43]
	v_mfma_f32_16x16x32_bf16 v[32:35], v[178:181], v[198:201], v[32:35]
	v_mfma_f32_16x16x32_bf16 v[24:27], v[170:173], v[206:209], v[24:27]
	v_mfma_f32_16x16x32_bf16 v[16:19], v[178:181], v[206:209], v[16:19]
	v_mfma_f32_16x16x32_bf16 v[8:11], v[170:173], v[214:217], v[8:11]
	v_mfma_f32_16x16x32_bf16 v[0:3], v[178:181], v[214:217], v[0:3]
	s_barrier
	s_setprio 0
	s_add_i32 s64, 0, 0x18000
	v_add_u32_e32 v146, s64, v149
	s_add_i32 s65, 0, 0x1c000
	ds_read_b128 v[128:131], v146
	ds_read_b128 v[154:157], v146 offset:1024
	ds_read_b128 v[158:161], v146 offset:2048
	ds_read_b128 v[162:165], v146 offset:3072
	v_add_u32_e32 v146, s65, v149
	ds_read_b128 v[166:169], v146
	ds_read_b128 v[170:173], v146 offset:1024
	ds_read_b128 v[174:177], v146 offset:2048
	ds_read_b128 v[178:181], v146 offset:3072
	s_add_u32 s10, s48, 0x40000
	s_addc_u32 s11, s49, 0
	s_mov_b32 m0, s53
	v_lshl_add_u64 v[224:225], s[10:11], 0, v[138:139]
	ds_read_b128 v[182:185], v153 offset:32768
	ds_read_b128 v[186:189], v153 offset:33792
	ds_read_b128 v[194:197], v153 offset:34816
	ds_read_b128 v[198:201], v153 offset:35840
	ds_read_b128 v[202:205], v153 offset:36864
	ds_read_b128 v[206:209], v153 offset:37888
	ds_read_b128 v[210:213], v153 offset:38912
	ds_read_b128 v[214:217], v153 offset:39936
	global_load_lds_dwordx4 v[224:225], off
	v_lshl_add_u64 v[224:225], s[10:11], 0, v[134:135]
	s_mov_b32 m0, s54
	s_nop 0
	global_load_lds_dwordx4 v[224:225], off
	s_setprio 1
	s_waitcnt vmcnt(8)
	s_waitcnt lgkmcnt(0)
	s_barrier
	v_mfma_f32_16x16x32_bf16 v[124:127], v[128:131], v[182:185], v[124:127]
	v_mfma_f32_16x16x32_bf16 v[116:119], v[158:161], v[182:185], v[116:119]
	v_mfma_f32_16x16x32_bf16 v[108:111], v[128:131], v[194:197], v[108:111]
	v_mfma_f32_16x16x32_bf16 v[100:103], v[158:161], v[194:197], v[100:103]
	v_mfma_f32_16x16x32_bf16 v[92:95], v[128:131], v[202:205], v[92:95]
	v_mfma_f32_16x16x32_bf16 v[84:87], v[158:161], v[202:205], v[84:87]
	v_mfma_f32_16x16x32_bf16 v[76:79], v[128:131], v[210:213], v[76:79]
	v_mfma_f32_16x16x32_bf16 v[68:71], v[158:161], v[210:213], v[68:71]
	v_mfma_f32_16x16x32_bf16 v[124:127], v[154:157], v[186:189], v[124:127]
	v_mfma_f32_16x16x32_bf16 v[116:119], v[162:165], v[186:189], v[116:119]
	v_mfma_f32_16x16x32_bf16 v[108:111], v[154:157], v[198:201], v[108:111]
	v_mfma_f32_16x16x32_bf16 v[100:103], v[162:165], v[198:201], v[100:103]
	v_mfma_f32_16x16x32_bf16 v[92:95], v[154:157], v[206:209], v[92:95]
	v_mfma_f32_16x16x32_bf16 v[84:87], v[162:165], v[206:209], v[84:87]
	v_mfma_f32_16x16x32_bf16 v[76:79], v[154:157], v[214:217], v[76:79]
	v_mfma_f32_16x16x32_bf16 v[68:71], v[162:165], v[214:217], v[68:71]
	s_setprio 0
	s_setprio 1
	v_mfma_f32_16x16x32_bf16 v[120:123], v[166:169], v[182:185], v[120:123]
	v_mfma_f32_16x16x32_bf16 v[112:115], v[174:177], v[182:185], v[112:115]
	v_mfma_f32_16x16x32_bf16 v[104:107], v[166:169], v[194:197], v[104:107]
	v_mfma_f32_16x16x32_bf16 v[96:99], v[174:177], v[194:197], v[96:99]
	v_mfma_f32_16x16x32_bf16 v[88:91], v[166:169], v[202:205], v[88:91]
	v_mfma_f32_16x16x32_bf16 v[80:83], v[174:177], v[202:205], v[80:83]
	v_mfma_f32_16x16x32_bf16 v[72:75], v[166:169], v[210:213], v[72:75]
	v_mfma_f32_16x16x32_bf16 v[64:67], v[174:177], v[210:213], v[64:67]
	v_mfma_f32_16x16x32_bf16 v[120:123], v[170:173], v[186:189], v[120:123]
	v_mfma_f32_16x16x32_bf16 v[112:115], v[178:181], v[186:189], v[112:115]
	v_mfma_f32_16x16x32_bf16 v[104:107], v[170:173], v[198:201], v[104:107]
	v_mfma_f32_16x16x32_bf16 v[96:99], v[178:181], v[198:201], v[96:99]
	v_mfma_f32_16x16x32_bf16 v[88:91], v[170:173], v[206:209], v[88:91]
	v_mfma_f32_16x16x32_bf16 v[80:83], v[178:181], v[206:209], v[80:83]
	v_mfma_f32_16x16x32_bf16 v[72:75], v[170:173], v[214:217], v[72:75]
	v_mfma_f32_16x16x32_bf16 v[64:67], v[178:181], v[214:217], v[64:67]
	s_barrier
; #define PG8_STAGE(bufoff, gbase, voff) do { _Pragma("unroll") for (int _i = 0; _i < 2; ++_i) \
;         __builtin_amdgcn_global_load_lds((const unsigned*)((const char*)(gbase) + (voff)[_i]), (PG8_LAS unsigned*)(lds + (bufoff) + ldsw + _i * 8192), 16, 0, 0); } while (0)
; #define PG8_LDA(dst, b, h) do { _Pragma("unroll") for (int m = 0; m < 4; ++m) _Pragma("unroll") for (int k = 0; k < 2; ++k) dst[m][k] = *(const PG8_LAS bf16x8*)(lds + PG8_SA(b, h) + aoff + m * 2048 + k * 1024); } while (0)
; #define PG8_MMA(ai, bj, At, Bt) do { __builtin_amdgcn_s_setprio(1); _Pragma("unroll") for (int m = 0; m < 4; ++m) _Pragma("unroll") for (int n = 0; n < 2; ++n) _Pragma("unroll") for (int k = 0; k < 2; ++k) \
;         acc[ai][bj][m][n] = __builtin_amdgcn_mfma_f32_16x16x32_bf16(Bt[n][k], At[m][k], acc[ai][bj][m][n], 0, 0, 0); __builtin_amdgcn_s_setprio(0); } while (0)
; #define PG8_WAIT_V(n) asm volatile("s_waitcnt vmcnt(" #n ")" ::: "memory")
; #define PG8_WAIT_L(n) asm volatile("s_waitcnt lgkmcnt(" #n ")" ::: "memory")
; #define PG8_BAR __builtin_amdgcn_s_barrier()
; #define PG8_SCHED __builtin_amdgcn_sched_barrier(0)
; template <class Epi, class Sched, bool ALIGN_EPI = false, bool SP2 = false>
; __device__ __forceinline__ void gemm_phase(PG8_LAS unsigned char* lds, const Gemm g, const Sched& S, const Epi& E) {
;     ...
;             PG8_LDA(At, 1, 1); PG8_STAGE(PG8_SB(1, 0), b3, voffB); PG8_STAGE(PG8_SB(1, 1), b3 + hstep, voffB); PG8_STAGE(PG8_SA(1, 0), a3, voffA);
;             PG8_WAIT_V(8); PG8_WAIT_L(0); PG8_BAR; PG8_MMA(1, 0, At, B0); PG8_MMA(1, 1, At, B1); PG8_BAR; PG8_SCHED;
;     ...
;         if constexpr (ALIGN_EPI) { if (wr == 0) PG8_BAR; }
	s_setprio 0
	s_add_i32 s10, s64, s19
	v_lshl_add_u64 v[190:191], v[190:191], 0, s[36:37]
	s_mov_b32 m0, s10
	ds_read_b128 v[182:185], v153 offset:49152
	ds_read_b128 v[186:189], v153 offset:50176
	ds_read_b128 v[194:197], v153 offset:51200
	ds_read_b128 v[198:201], v153 offset:52224
	ds_read_b128 v[202:205], v153 offset:53248
	ds_read_b128 v[206:209], v153 offset:54272
	ds_read_b128 v[210:213], v153 offset:55296
	ds_read_b128 v[214:217], v153 offset:56320
	global_load_lds_dwordx4 v[190:191], off
	s_add_i32 m0, s10, 0x2000
	s_add_u32 s10, s46, 0x40080
	v_lshl_add_u64 v[190:191], v[218:219], 0, s[36:37]
	s_addc_u32 s11, s47, 0
	s_add_i32 s46, s65, s19
	global_load_lds_dwordx4 v[190:191], off
	v_lshl_add_u64 v[190:191], s[10:11], 0, v[136:137]
	s_mov_b32 m0, s46
	s_nop 0
	global_load_lds_dwordx4 v[190:191], off
	v_lshl_add_u64 v[190:191], s[10:11], 0, v[132:133]
	s_add_i32 m0, s46, 0x2000
	s_nop 0
	global_load_lds_dwordx4 v[190:191], off
	v_lshl_add_u64 v[190:191], v[220:221], 0, s[36:37]
	s_mov_b32 m0, s20
	s_nop 0
	global_load_lds_dwordx4 v[190:191], off
	v_lshl_add_u64 v[190:191], v[222:223], 0, s[36:37]
	s_mov_b32 m0, s55
	s_nop 0
	global_load_lds_dwordx4 v[190:191], off
	s_setprio 1
	s_waitcnt vmcnt(8)
	s_waitcnt lgkmcnt(0)
	s_barrier
	v_mfma_f32_16x16x32_bf16 v[60:63], v[128:131], v[182:185], v[60:63]
	v_mfma_f32_16x16x32_bf16 v[52:55], v[158:161], v[182:185], v[52:55]
	v_mfma_f32_16x16x32_bf16 v[44:47], v[128:131], v[194:197], v[44:47]
	v_mfma_f32_16x16x32_bf16 v[36:39], v[158:161], v[194:197], v[36:39]
	v_mfma_f32_16x16x32_bf16 v[28:31], v[128:131], v[202:205], v[28:31]
	v_mfma_f32_16x16x32_bf16 v[20:23], v[158:161], v[202:205], v[20:23]
	v_mfma_f32_16x16x32_bf16 v[12:15], v[128:131], v[210:213], v[12:15]
	v_mfma_f32_16x16x32_bf16 v[4:7], v[158:161], v[210:213], v[4:7]
	v_mfma_f32_16x16x32_bf16 v[60:63], v[154:157], v[186:189], v[60:63]
	v_mfma_f32_16x16x32_bf16 v[52:55], v[162:165], v[186:189], v[52:55]
	v_mfma_f32_16x16x32_bf16 v[44:47], v[154:157], v[198:201], v[44:47]
	v_mfma_f32_16x16x32_bf16 v[36:39], v[162:165], v[198:201], v[36:39]
	v_mfma_f32_16x16x32_bf16 v[28:31], v[154:157], v[206:209], v[28:31]
	v_mfma_f32_16x16x32_bf16 v[20:23], v[162:165], v[206:209], v[20:23]
	v_mfma_f32_16x16x32_bf16 v[12:15], v[154:157], v[214:217], v[12:15]
	v_mfma_f32_16x16x32_bf16 v[4:7], v[162:165], v[214:217], v[4:7]
	s_setprio 0
	s_setprio 1
	v_mfma_f32_16x16x32_bf16 v[56:59], v[166:169], v[182:185], v[56:59]
	v_mfma_f32_16x16x32_bf16 v[48:51], v[174:177], v[182:185], v[48:51]
	v_mfma_f32_16x16x32_bf16 v[40:43], v[166:169], v[194:197], v[40:43]
	v_mfma_f32_16x16x32_bf16 v[32:35], v[174:177], v[194:197], v[32:35]
	v_mfma_f32_16x16x32_bf16 v[24:27], v[166:169], v[202:205], v[24:27]
	v_mfma_f32_16x16x32_bf16 v[16:19], v[174:177], v[202:205], v[16:19]
	v_mfma_f32_16x16x32_bf16 v[8:11], v[166:169], v[210:213], v[8:11]
	v_mfma_f32_16x16x32_bf16 v[0:3], v[174:177], v[210:213], v[0:3]
	v_mfma_f32_16x16x32_bf16 v[56:59], v[170:173], v[186:189], v[56:59]
	v_mfma_f32_16x16x32_bf16 v[48:51], v[178:181], v[186:189], v[48:51]
	v_mfma_f32_16x16x32_bf16 v[40:43], v[170:173], v[198:201], v[40:43]
	v_mfma_f32_16x16x32_bf16 v[32:35], v[178:181], v[198:201], v[32:35]
	v_mfma_f32_16x16x32_bf16 v[24:27], v[170:173], v[206:209], v[24:27]
	v_mfma_f32_16x16x32_bf16 v[16:19], v[178:181], v[206:209], v[16:19]
	v_mfma_f32_16x16x32_bf16 v[8:11], v[170:173], v[214:217], v[8:11]
	v_mfma_f32_16x16x32_bf16 v[0:3], v[178:181], v[214:217], v[0:3]
	s_barrier
	s_setprio 0
	s_add_i32 s63, s63, 2
	s_add_u32 s44, s44, 0x100
	s_addc_u32 s45, s45, 0
	s_add_u32 s61, s61, 0x100
	s_addc_u32 s62, s62, 0
	s_cmp_gt_u32 s63, 13
	s_cbranch_scc0 .LBB0_577
	s_and_b64 vcc, exec, s[24:25]
	s_cbranch_vccz .LBB0_580
	s_barrier
